# final RMSNorm fused into the PLE-gate GEMM epilogue: h3 kept in registers, per-row-set arrival counters, pp row pitch 4096 B, P7 pass and last grid barrier removed
# speedup vs baseline: 1.0958x; 1.0152x over previous
.LBB0_1962:
	s_and_b32 s20, s14, 3
	s_mov_b64 s[14:15], 0x80
	s_add_i32 m0, s37, 0x18000
	v_lshl_add_u64 v[6:7], v[6:7], 0, s[14:15]
	s_sub_i32 s3, s70, s3
	s_lshl_b32 s17, s9, 13
	s_lshl_b32 s21, s20, 12
	s_waitcnt vmcnt(2)
	s_barrier
	global_load_lds_dwordx4 v[6:7], off
	v_lshl_add_u64 v[4:5], v[4:5], 0, s[14:15]
	s_add_i32 m0, s37, 0x1a000
	s_add_i32 s68, s37, 0x8000
	s_add_i32 s69, s37, 0xa000
	global_load_lds_dwordx4 v[4:5], off
	v_lshl_add_u64 v[0:1], v[0:1], 0, s[14:15]
	s_mov_b32 m0, s68
	s_add_u32 s18, s38, 0x10080
	global_load_lds_dwordx4 v[0:1], off
	v_lshl_add_u64 v[0:1], v[2:3], 0, s[14:15]
	s_mov_b32 m0, s69
	s_addc_u32 s19, s39, 0
	global_load_lds_dwordx4 v[0:1], off
	s_add_i32 m0, s37, 0x1c000
	v_lshl_add_u64 v[0:1], s[18:19], 0, v[132:133]
	global_load_lds_dwordx4 v[0:1], off
	v_lshl_add_u64 v[0:1], s[18:19], 0, v[128:129]
	s_add_i32 m0, s37, 0x1e000
	s_cmpk_lt_u32 s16, 0x100
	global_load_lds_dwordx4 v[0:1], off
	v_bfe_u32 v0, v8, 4, 2
	v_and_b32_e32 v1, 15, v8
	v_lshlrev_b32_e32 v2, 3, v0
	v_lshlrev_b32_e32 v0, 4, v0
	v_lshl_or_b32 v142, s9, 6, v1
	v_lshl_or_b32 v0, v1, 6, v0
	v_lshlrev_b32_e32 v1, 2, v8
	v_and_b32_e32 v1, 32, v1
	s_waitcnt vmcnt(6)
	v_bitop3_b32 v3, v0, s17, v1 bitop3:0xde
	v_bitop3_b32 v143, v0, s21, v1 bitop3:0xde
	s_cselect_b64 s[16:17], -1, 0
	s_add_i32 s73, 0, 0x10000
	s_add_i32 s74, 0, 0x14000
	s_sext_i32_i8 s79, s8
	s_ashr_i32 s72, s3, 31
	v_lshl_or_b32 v144, s20, 5, v2
	v_mov_b64_e32 v[136:137], 0x110
	v_mov_b64_e32 v[138:139], 0x10f
	v_add_u32_e32 v145, s73, v143
	v_add_u32_e32 v146, s74, v143
	v_add_u32_e32 v147, 0, v3
	s_mov_b64 s[18:19], 0x80000
	s_mov_b32 s75, 0x80000
	s_mov_b64 s[20:21], 0x90000
	s_mov_b32 s76, 0x90000
	s_mov_b64 s[22:23], 0xa0000
	s_mov_b32 s77, 0xa0000
	s_mov_b64 s[24:25], 0xb0000
	s_mov_b32 s78, 0xb0000
	s_barrier
	s_waitcnt vmcnt(0)
	s_branch .LBB0_1965

.LBB0_1973:
	v_lshl_add_u32 v148, s36, 8, v142
	v_lshl_or_b32 v140, s79, 8, v144
	v_ashrrev_i32_e32 v149, 31, v148
	v_ashrrev_i32_e32 v141, 31, v140
	v_lshlrev_b64 v[150:151], 12, v[148:149]
	v_lshl_add_u64 v[150:151], s[12:13], 0, v[150:151]
	v_lshlrev_b64 v[152:153], 1, v[140:141]
	v_lshl_add_u64 v[140:141], v[150:151], 0, v[152:153]
	v_cvt_pk_bf16_f32 v124, v124, v125
	v_cvt_pk_bf16_f32 v125, v126, v127
	v_cvt_pk_bf16_f32 v126, v120, v121
	v_cvt_pk_bf16_f32 v127, v122, v123
	global_store_dwordx4 v[140:141], v[124:127], off
	v_cvt_pk_bf16_f32 v112, v112, v113
	v_cvt_pk_bf16_f32 v113, v114, v115
	v_cvt_pk_bf16_f32 v114, v104, v105
	v_or_b32_e32 v104, 16, v148
	v_ashrrev_i32_e32 v105, 31, v104
	v_lshlrev_b64 v[104:105], 12, v[104:105]
	v_lshl_add_u64 v[104:105], s[12:13], 0, v[104:105]
	v_cvt_pk_bf16_f32 v115, v106, v107
	global_store_dwordx4 v[140:141], v[112:115], off offset:256
	s_nop 1
	v_lshl_add_u64 v[112:113], v[104:105], 0, v[152:153]
	v_cvt_pk_bf16_f32 v104, v116, v117
	v_cvt_pk_bf16_f32 v105, v118, v119
	v_cvt_pk_bf16_f32 v106, v108, v109
	v_cvt_pk_bf16_f32 v107, v110, v111
	global_store_dwordx4 v[112:113], v[104:107], off
	v_cvt_pk_bf16_f32 v96, v96, v97
	v_cvt_pk_bf16_f32 v97, v98, v99
	v_cvt_pk_bf16_f32 v98, v88, v89
	v_or_b32_e32 v88, 32, v148
	v_ashrrev_i32_e32 v89, 31, v88
	v_lshlrev_b64 v[88:89], 12, v[88:89]
	v_lshl_add_u64 v[88:89], s[12:13], 0, v[88:89]
	v_cvt_pk_bf16_f32 v99, v90, v91
	global_store_dwordx4 v[112:113], v[96:99], off offset:256
	s_nop 1
	v_lshl_add_u64 v[96:97], v[88:89], 0, v[152:153]
	v_cvt_pk_bf16_f32 v88, v100, v101
	v_cvt_pk_bf16_f32 v89, v102, v103
	v_cvt_pk_bf16_f32 v90, v92, v93
	v_cvt_pk_bf16_f32 v91, v94, v95
	global_store_dwordx4 v[96:97], v[88:91], off
	v_cvt_pk_bf16_f32 v80, v80, v81
	v_cvt_pk_bf16_f32 v81, v82, v83
	v_cvt_pk_bf16_f32 v82, v72, v73
	v_or_b32_e32 v72, 48, v148
	v_ashrrev_i32_e32 v73, 31, v72
	v_lshlrev_b64 v[72:73], 12, v[72:73]
	v_lshl_add_u64 v[72:73], s[12:13], 0, v[72:73]
	v_cvt_pk_bf16_f32 v83, v74, v75
	global_store_dwordx4 v[96:97], v[80:83], off offset:256
	s_nop 1
	v_lshl_add_u64 v[80:81], v[72:73], 0, v[152:153]
	v_cvt_pk_bf16_f32 v72, v84, v85
	v_cvt_pk_bf16_f32 v73, v86, v87
	v_cvt_pk_bf16_f32 v74, v76, v77
	v_cvt_pk_bf16_f32 v75, v78, v79
	global_store_dwordx4 v[80:81], v[72:75], off
	v_cvt_pk_bf16_f32 v68, v68, v69
	v_cvt_pk_bf16_f32 v69, v70, v71
	v_cvt_pk_bf16_f32 v70, v64, v65
	v_cvt_pk_bf16_f32 v71, v66, v67
	global_store_dwordx4 v[80:81], v[68:71], off offset:256
	v_cvt_pk_bf16_f32 v60, v60, v61
	v_cvt_pk_bf16_f32 v61, v62, v63
	v_cvt_pk_bf16_f32 v62, v56, v57
	v_add_co_u32_e32 v56, vcc, s75, v140
	v_lshl_add_u64 v[64:65], v[140:141], 0, s[18:19]
	s_nop 0
	v_addc_co_u32_e32 v57, vcc, 0, v141, vcc
	v_cvt_pk_bf16_f32 v63, v58, v59
	global_store_dwordx4 v[56:57], v[60:63], off
	v_cvt_pk_bf16_f32 v48, v48, v49
	v_cvt_pk_bf16_f32 v49, v50, v51
	v_cvt_pk_bf16_f32 v50, v40, v41
	v_cvt_pk_bf16_f32 v51, v42, v43
	global_store_dwordx4 v[64:65], v[48:51], off offset:256
	v_cvt_pk_bf16_f32 v40, v52, v53
	v_cvt_pk_bf16_f32 v41, v54, v55
	v_cvt_pk_bf16_f32 v42, v44, v45
	v_add_co_u32_e32 v44, vcc, s76, v140
	s_nop 0
	v_lshl_add_u64 v[48:49], v[140:141], 0, s[20:21]
	v_addc_co_u32_e32 v45, vcc, 0, v141, vcc
	v_cvt_pk_bf16_f32 v43, v46, v47
	global_store_dwordx4 v[44:45], v[40:43], off
	v_cvt_pk_bf16_f32 v32, v32, v33
	v_cvt_pk_bf16_f32 v33, v34, v35
	v_cvt_pk_bf16_f32 v34, v24, v25
	v_cvt_pk_bf16_f32 v35, v26, v27
	global_store_dwordx4 v[48:49], v[32:35], off offset:256
	v_cvt_pk_bf16_f32 v24, v36, v37
	v_cvt_pk_bf16_f32 v25, v38, v39
	v_cvt_pk_bf16_f32 v26, v28, v29
	v_add_co_u32_e32 v28, vcc, s77, v140
	s_nop 0
	v_lshl_add_u64 v[32:33], v[140:141], 0, s[22:23]
	v_addc_co_u32_e32 v29, vcc, 0, v141, vcc
	v_cvt_pk_bf16_f32 v27, v30, v31
	global_store_dwordx4 v[28:29], v[24:27], off
	v_cvt_pk_bf16_f32 v16, v16, v17
	v_cvt_pk_bf16_f32 v17, v18, v19
	v_cvt_pk_bf16_f32 v18, v8, v9
	v_cvt_pk_bf16_f32 v19, v10, v11
	global_store_dwordx4 v[32:33], v[16:19], off offset:256
	v_cvt_pk_bf16_f32 v8, v20, v21
	v_cvt_pk_bf16_f32 v9, v22, v23
	v_cvt_pk_bf16_f32 v10, v12, v13
	v_add_co_u32_e32 v12, vcc, s78, v140
	s_nop 0
	v_lshl_add_u64 v[16:17], v[140:141], 0, s[24:25]
	v_addc_co_u32_e32 v13, vcc, 0, v141, vcc
	v_cvt_pk_bf16_f32 v11, v14, v15
	global_store_dwordx4 v[12:13], v[8:11], off
	v_cvt_pk_bf16_f32 v4, v4, v5
	v_cvt_pk_bf16_f32 v5, v6, v7
	v_cvt_pk_bf16_f32 v6, v0, v1
	v_cvt_pk_bf16_f32 v7, v2, v3
	global_store_dwordx4 v[16:17], v[4:7], off offset:256
	s_andn2_b64 vcc, exec, s[8:9]
	s_mov_b64 s[8:9], -1
	s_cbranch_vccnz .LBB0_1964

.LBB0_2043:
	s_cmp_eq_u32 s97, 1
	s_cbranch_scc1 .Lwh_p6_epi
	v_lshl_add_u32 v146, s36, 8, v152
	v_lshl_or_b32 v144, s34, 8, v154
	s_load_dwordx2 s[98:99], s[0:1], 0x118
	v_lshlrev_b32_e32 v145, 12, v146
	v_lshl_add_u32 v147, v144, 1, v145
	v_lshl_add_u32 v145, v144, 2, v145
	v_lshlrev_b32_e32 v148, 3, v146
	v_xor_b32_e32 v149, 16, v158
	v_lshlrev_b32_e32 v149, 2, v149
	v_xor_b32_e32 v150, 32, v158
	v_lshlrev_b32_e32 v150, 2, v150
	global_load_dwordx2 v[160:161], v148, s[18:19]
	global_load_dwordx4 v[162:165], v147, s[12:13]
	global_load_dwordx4 v[166:169], v147, s[12:13] offset:256
	global_load_dwordx4 v[170:173], v145, s[16:17]
	global_load_dwordx4 v[176:179], v145, s[16:17] offset:16
	global_load_dwordx4 v[180:183], v145, s[16:17] offset:512
	global_load_dwordx4 v[184:187], v145, s[16:17] offset:528
	v_add_u32_e32 v214, 0x10000, v145
	v_add_u32_e32 v215, 0x10000, v147
	v_add_u32_e32 v216, 0x80, v148
	global_load_dwordx2 v[188:189], v216, s[18:19]
	global_load_dwordx4 v[190:193], v215, s[12:13]
	global_load_dwordx4 v[194:197], v215, s[12:13] offset:256
	global_load_dwordx4 v[198:201], v214, s[16:17]
	global_load_dwordx4 v[202:205], v214, s[16:17] offset:16
	global_load_dwordx4 v[206:209], v214, s[16:17] offset:512
	global_load_dwordx4 v[210:213], v214, s[16:17] offset:528
	s_waitcnt vmcnt(7)
	v_ffbh_u32_e32 v151, v161
	v_min_u32_e32 v151, 32, v151
	v_lshlrev_b64 v[160:161], v151, v[160:161]
	v_sub_u32_e32 v151, 32, v151
	v_min_u32_e32 v160, 1, v160
	v_or_b32_e32 v160, v161, v160
	v_cvt_f32_u32_e32 v160, v160
	v_ldexp_f32 v160, v160, v151
	v_fmamk_f32 v160, v160, 0x30800000, v159
	v_mul_f32_e32 v161, 0x4b800000, v160
	v_cmp_gt_f32_e32 vcc, s57, v160
	s_nop 1
	v_cndmask_b32_e32 v160, v160, v161, vcc
	v_rsq_f32_e32 v160, v160
	s_nop 0
	v_mul_f32_e32 v161, 0x45800000, v160
	v_cndmask_b32_e32 v217, v160, v161, vcc
	v_mul_f32_e64 v124, v124, -v217
	v_mul_f32_e64 v125, v125, -v217
	v_mul_f32_e64 v126, v126, -v217
	v_mul_f32_e64 v127, v127, -v217
	v_mul_f32_e64 v120, v120, -v217
	v_mul_f32_e64 v121, v121, -v217
	v_mul_f32_e64 v122, v122, -v217
	v_mul_f32_e64 v123, v123, -v217
	v_mul_f32_e64 v116, v116, -v217
	v_mul_f32_e64 v117, v117, -v217
	v_mul_f32_e64 v118, v118, -v217
	v_mul_f32_e64 v119, v119, -v217
	v_mul_f32_e64 v112, v112, -v217
	v_mul_f32_e64 v113, v113, -v217
	v_mul_f32_e64 v114, v114, -v217
	v_mul_f32_e64 v115, v115, -v217
	v_mul_f32_e32 v124, 0x3fb8aa3b, v124
	v_mul_f32_e32 v125, 0x3fb8aa3b, v125
	v_mul_f32_e32 v126, 0x3fb8aa3b, v126
	v_mul_f32_e32 v127, 0x3fb8aa3b, v127
	v_mul_f32_e32 v120, 0x3fb8aa3b, v120
	v_mul_f32_e32 v121, 0x3fb8aa3b, v121
	v_mul_f32_e32 v122, 0x3fb8aa3b, v122
	v_mul_f32_e32 v123, 0x3fb8aa3b, v123
	v_mul_f32_e32 v116, 0x3fb8aa3b, v116
	v_mul_f32_e32 v117, 0x3fb8aa3b, v117
	v_mul_f32_e32 v118, 0x3fb8aa3b, v118
	v_mul_f32_e32 v119, 0x3fb8aa3b, v119
	v_mul_f32_e32 v112, 0x3fb8aa3b, v112
	v_mul_f32_e32 v113, 0x3fb8aa3b, v113
	v_mul_f32_e32 v114, 0x3fb8aa3b, v114
	v_mul_f32_e32 v115, 0x3fb8aa3b, v115
	v_exp_f32_e32 v124, v124
	v_exp_f32_e32 v125, v125
	v_exp_f32_e32 v126, v126
	v_exp_f32_e32 v127, v127
	v_exp_f32_e32 v120, v120
	v_exp_f32_e32 v121, v121
	v_exp_f32_e32 v122, v122
	v_exp_f32_e32 v123, v123
	v_exp_f32_e32 v116, v116
	v_exp_f32_e32 v117, v117
	v_exp_f32_e32 v118, v118
	v_exp_f32_e32 v119, v119
	v_exp_f32_e32 v112, v112
	v_exp_f32_e32 v113, v113
	v_exp_f32_e32 v114, v114
	v_exp_f32_e32 v115, v115
	v_add_f32_e32 v124, 1.0, v124
	v_add_f32_e32 v125, 1.0, v125
	v_add_f32_e32 v126, 1.0, v126
	v_add_f32_e32 v127, 1.0, v127
	v_add_f32_e32 v120, 1.0, v120
	v_add_f32_e32 v121, 1.0, v121
	v_add_f32_e32 v122, 1.0, v122
	v_add_f32_e32 v123, 1.0, v123
	v_add_f32_e32 v116, 1.0, v116
	v_add_f32_e32 v117, 1.0, v117
	v_add_f32_e32 v118, 1.0, v118
	v_add_f32_e32 v119, 1.0, v119
	v_add_f32_e32 v112, 1.0, v112
	v_add_f32_e32 v113, 1.0, v113
	v_add_f32_e32 v114, 1.0, v114
	v_add_f32_e32 v115, 1.0, v115
	v_rcp_f32_e32 v124, v124
	v_rcp_f32_e32 v125, v125
	v_rcp_f32_e32 v126, v126
	v_rcp_f32_e32 v127, v127
	v_rcp_f32_e32 v120, v120
	v_rcp_f32_e32 v121, v121
	v_rcp_f32_e32 v122, v122
	v_rcp_f32_e32 v123, v123
	v_rcp_f32_e32 v116, v116
	v_rcp_f32_e32 v117, v117
	v_rcp_f32_e32 v118, v118
	v_rcp_f32_e32 v119, v119
	v_rcp_f32_e32 v112, v112
	v_rcp_f32_e32 v113, v113
	v_rcp_f32_e32 v114, v114
	v_rcp_f32_e32 v115, v115
	s_nop 0
	v_lshlrev_b32_e32 v151, 16, v162
	v_fma_f32 v124, v124, v151, v170
	v_mul_f32_e32 v175, v124, v124
	v_and_b32_e32 v151, 0xffff0000, v162
	v_fma_f32 v125, v125, v151, v171
	v_fmac_f32_e32 v175, v125, v125
	v_lshlrev_b32_e32 v151, 16, v163
	v_fma_f32 v126, v126, v151, v172
	v_fmac_f32_e32 v175, v126, v126
	v_and_b32_e32 v151, 0xffff0000, v163
	v_fma_f32 v127, v127, v151, v173
	v_fmac_f32_e32 v175, v127, v127
	v_lshlrev_b32_e32 v151, 16, v164
	v_fma_f32 v120, v120, v151, v176
	v_fmac_f32_e32 v175, v120, v120
	v_and_b32_e32 v151, 0xffff0000, v164
	v_fma_f32 v121, v121, v151, v177
	v_fmac_f32_e32 v175, v121, v121
	v_lshlrev_b32_e32 v151, 16, v165
	v_fma_f32 v122, v122, v151, v178
	v_fmac_f32_e32 v175, v122, v122
	v_and_b32_e32 v151, 0xffff0000, v165
	v_fma_f32 v123, v123, v151, v179
	v_fmac_f32_e32 v175, v123, v123
	v_lshlrev_b32_e32 v151, 16, v166
	v_fma_f32 v116, v116, v151, v180
	v_fmac_f32_e32 v175, v116, v116
	v_and_b32_e32 v151, 0xffff0000, v166
	v_fma_f32 v117, v117, v151, v181
	v_fmac_f32_e32 v175, v117, v117
	v_lshlrev_b32_e32 v151, 16, v167
	v_fma_f32 v118, v118, v151, v182
	v_fmac_f32_e32 v175, v118, v118
	v_and_b32_e32 v151, 0xffff0000, v167
	v_fma_f32 v119, v119, v151, v183
	v_fmac_f32_e32 v175, v119, v119
	v_lshlrev_b32_e32 v151, 16, v168
	v_fma_f32 v112, v112, v151, v184
	v_fmac_f32_e32 v175, v112, v112
	v_and_b32_e32 v151, 0xffff0000, v168
	v_fma_f32 v113, v113, v151, v185
	v_fmac_f32_e32 v175, v113, v113
	v_lshlrev_b32_e32 v151, 16, v169
	v_fma_f32 v114, v114, v151, v186
	v_fmac_f32_e32 v175, v114, v114
	v_and_b32_e32 v151, 0xffff0000, v169
	v_fma_f32 v115, v115, v151, v187
	v_fmac_f32_e32 v175, v115, v115
	ds_bpermute_b32 v151, v149, v175
	s_waitcnt lgkmcnt(0)
	v_add_f32_e32 v175, v175, v151
	ds_bpermute_b32 v151, v150, v175
	s_waitcnt lgkmcnt(0)
	v_add_f32_e32 v175, v175, v151
	v_mul_f32_e32 v218, 0x49800000, v175
	v_trunc_f32_e32 v218, v218
	v_mul_f32_e32 v219, 0x2f800000, v218
	v_floor_f32_e32 v219, v219
	v_fmac_f32_e32 v218, 0xcf800000, v219
	v_cvt_u32_f32_e32 v218, v218
	v_cvt_u32_f32_e32 v219, v219
	s_mov_b64 exec, s[6:7]
	global_atomic_add_x2 v148, v[218:219], s[14:15]
	s_mov_b64 exec, -1
	v_add_u32_e32 v214, 0x20000, v145
	v_add_u32_e32 v215, 0x20000, v147
	v_add_u32_e32 v216, 0x100, v148
	global_load_dwordx2 v[160:161], v216, s[18:19]
	global_load_dwordx4 v[162:165], v215, s[12:13]
	global_load_dwordx4 v[166:169], v215, s[12:13] offset:256
	global_load_dwordx4 v[170:173], v214, s[16:17]
	global_load_dwordx4 v[176:179], v214, s[16:17] offset:16
	global_load_dwordx4 v[180:183], v214, s[16:17] offset:512
	global_load_dwordx4 v[184:187], v214, s[16:17] offset:528
	s_waitcnt vmcnt(8)
	v_ffbh_u32_e32 v151, v189
	v_min_u32_e32 v151, 32, v151
	v_lshlrev_b64 v[188:189], v151, v[188:189]
	v_sub_u32_e32 v151, 32, v151
	v_min_u32_e32 v188, 1, v188
	v_or_b32_e32 v188, v189, v188
	v_cvt_f32_u32_e32 v188, v188
	v_ldexp_f32 v188, v188, v151
	v_fmamk_f32 v188, v188, 0x30800000, v159
	v_mul_f32_e32 v189, 0x4b800000, v188
	v_cmp_gt_f32_e32 vcc, s57, v188
	s_nop 1
	v_cndmask_b32_e32 v188, v188, v189, vcc
	v_rsq_f32_e32 v188, v188
	s_nop 0
	v_mul_f32_e32 v189, 0x45800000, v188
	v_cndmask_b32_e32 v217, v188, v189, vcc
	v_mul_f32_e64 v108, v108, -v217
	v_mul_f32_e64 v109, v109, -v217
	v_mul_f32_e64 v110, v110, -v217
	v_mul_f32_e64 v111, v111, -v217
	v_mul_f32_e64 v104, v104, -v217
	v_mul_f32_e64 v105, v105, -v217
	v_mul_f32_e64 v106, v106, -v217
	v_mul_f32_e64 v107, v107, -v217
	v_mul_f32_e64 v100, v100, -v217
	v_mul_f32_e64 v101, v101, -v217
	v_mul_f32_e64 v102, v102, -v217
	v_mul_f32_e64 v103, v103, -v217
	v_mul_f32_e64 v96, v96, -v217
	v_mul_f32_e64 v97, v97, -v217
	v_mul_f32_e64 v98, v98, -v217
	v_mul_f32_e64 v99, v99, -v217
	v_mul_f32_e32 v108, 0x3fb8aa3b, v108
	v_mul_f32_e32 v109, 0x3fb8aa3b, v109
	v_mul_f32_e32 v110, 0x3fb8aa3b, v110
	v_mul_f32_e32 v111, 0x3fb8aa3b, v111
	v_mul_f32_e32 v104, 0x3fb8aa3b, v104
	v_mul_f32_e32 v105, 0x3fb8aa3b, v105
	v_mul_f32_e32 v106, 0x3fb8aa3b, v106
	v_mul_f32_e32 v107, 0x3fb8aa3b, v107
	v_mul_f32_e32 v100, 0x3fb8aa3b, v100
	v_mul_f32_e32 v101, 0x3fb8aa3b, v101
	v_mul_f32_e32 v102, 0x3fb8aa3b, v102
	v_mul_f32_e32 v103, 0x3fb8aa3b, v103
	v_mul_f32_e32 v96, 0x3fb8aa3b, v96
	v_mul_f32_e32 v97, 0x3fb8aa3b, v97
	v_mul_f32_e32 v98, 0x3fb8aa3b, v98
	v_mul_f32_e32 v99, 0x3fb8aa3b, v99
	v_exp_f32_e32 v108, v108
	v_exp_f32_e32 v109, v109
	v_exp_f32_e32 v110, v110
	v_exp_f32_e32 v111, v111
	v_exp_f32_e32 v104, v104
	v_exp_f32_e32 v105, v105
	v_exp_f32_e32 v106, v106
	v_exp_f32_e32 v107, v107
	v_exp_f32_e32 v100, v100
	v_exp_f32_e32 v101, v101
	v_exp_f32_e32 v102, v102
	v_exp_f32_e32 v103, v103
	v_exp_f32_e32 v96, v96
	v_exp_f32_e32 v97, v97
	v_exp_f32_e32 v98, v98
	v_exp_f32_e32 v99, v99
	v_add_f32_e32 v108, 1.0, v108
	v_add_f32_e32 v109, 1.0, v109
	v_add_f32_e32 v110, 1.0, v110
	v_add_f32_e32 v111, 1.0, v111
	v_add_f32_e32 v104, 1.0, v104
	v_add_f32_e32 v105, 1.0, v105
	v_add_f32_e32 v106, 1.0, v106
	v_add_f32_e32 v107, 1.0, v107
	v_add_f32_e32 v100, 1.0, v100
	v_add_f32_e32 v101, 1.0, v101
	v_add_f32_e32 v102, 1.0, v102
	v_add_f32_e32 v103, 1.0, v103
	v_add_f32_e32 v96, 1.0, v96
	v_add_f32_e32 v97, 1.0, v97
	v_add_f32_e32 v98, 1.0, v98
	v_add_f32_e32 v99, 1.0, v99
	v_rcp_f32_e32 v108, v108
	v_rcp_f32_e32 v109, v109
	v_rcp_f32_e32 v110, v110
	v_rcp_f32_e32 v111, v111
	v_rcp_f32_e32 v104, v104
	v_rcp_f32_e32 v105, v105
	v_rcp_f32_e32 v106, v106
	v_rcp_f32_e32 v107, v107
	v_rcp_f32_e32 v100, v100
	v_rcp_f32_e32 v101, v101
	v_rcp_f32_e32 v102, v102
	v_rcp_f32_e32 v103, v103
	v_rcp_f32_e32 v96, v96
	v_rcp_f32_e32 v97, v97
	v_rcp_f32_e32 v98, v98
	v_rcp_f32_e32 v99, v99
	s_nop 0
	v_lshlrev_b32_e32 v151, 16, v190
	v_fma_f32 v108, v108, v151, v198
	v_mul_f32_e32 v175, v108, v108
	v_and_b32_e32 v151, 0xffff0000, v190
	v_fma_f32 v109, v109, v151, v199
	v_fmac_f32_e32 v175, v109, v109
	v_lshlrev_b32_e32 v151, 16, v191
	v_fma_f32 v110, v110, v151, v200
	v_fmac_f32_e32 v175, v110, v110
	v_and_b32_e32 v151, 0xffff0000, v191
	v_fma_f32 v111, v111, v151, v201
	v_fmac_f32_e32 v175, v111, v111
	v_lshlrev_b32_e32 v151, 16, v192
	v_fma_f32 v104, v104, v151, v202
	v_fmac_f32_e32 v175, v104, v104
	v_and_b32_e32 v151, 0xffff0000, v192
	v_fma_f32 v105, v105, v151, v203
	v_fmac_f32_e32 v175, v105, v105
	v_lshlrev_b32_e32 v151, 16, v193
	v_fma_f32 v106, v106, v151, v204
	v_fmac_f32_e32 v175, v106, v106
	v_and_b32_e32 v151, 0xffff0000, v193
	v_fma_f32 v107, v107, v151, v205
	v_fmac_f32_e32 v175, v107, v107
	v_lshlrev_b32_e32 v151, 16, v194
	v_fma_f32 v100, v100, v151, v206
	v_fmac_f32_e32 v175, v100, v100
	v_and_b32_e32 v151, 0xffff0000, v194
	v_fma_f32 v101, v101, v151, v207
	v_fmac_f32_e32 v175, v101, v101
	v_lshlrev_b32_e32 v151, 16, v195
	v_fma_f32 v102, v102, v151, v208
	v_fmac_f32_e32 v175, v102, v102
	v_and_b32_e32 v151, 0xffff0000, v195
	v_fma_f32 v103, v103, v151, v209
	v_fmac_f32_e32 v175, v103, v103
	v_lshlrev_b32_e32 v151, 16, v196
	v_fma_f32 v96, v96, v151, v210
	v_fmac_f32_e32 v175, v96, v96
	v_and_b32_e32 v151, 0xffff0000, v196
	v_fma_f32 v97, v97, v151, v211
	v_fmac_f32_e32 v175, v97, v97
	v_lshlrev_b32_e32 v151, 16, v197
	v_fma_f32 v98, v98, v151, v212
	v_fmac_f32_e32 v175, v98, v98
	v_and_b32_e32 v151, 0xffff0000, v197
	v_fma_f32 v99, v99, v151, v213
	v_fmac_f32_e32 v175, v99, v99
	ds_bpermute_b32 v151, v149, v175
	s_waitcnt lgkmcnt(0)
	v_add_f32_e32 v175, v175, v151
	ds_bpermute_b32 v151, v150, v175
	s_waitcnt lgkmcnt(0)
	v_add_f32_e32 v175, v175, v151
	v_mul_f32_e32 v218, 0x49800000, v175
	v_trunc_f32_e32 v218, v218
	v_mul_f32_e32 v219, 0x2f800000, v218
	v_floor_f32_e32 v219, v219
	v_fmac_f32_e32 v218, 0xcf800000, v219
	v_cvt_u32_f32_e32 v218, v218
	v_cvt_u32_f32_e32 v219, v219
	v_add_u32_e32 v151, 0x80, v148
	s_mov_b64 exec, s[6:7]
	global_atomic_add_x2 v151, v[218:219], s[14:15]
	s_mov_b64 exec, -1
	v_add_u32_e32 v214, 0x30000, v145
	v_add_u32_e32 v215, 0x30000, v147
	v_add_u32_e32 v216, 0x180, v148
	global_load_dwordx2 v[188:189], v216, s[18:19]
	global_load_dwordx4 v[190:193], v215, s[12:13]
	global_load_dwordx4 v[194:197], v215, s[12:13] offset:256
	global_load_dwordx4 v[198:201], v214, s[16:17]
	global_load_dwordx4 v[202:205], v214, s[16:17] offset:16
	global_load_dwordx4 v[206:209], v214, s[16:17] offset:512
	global_load_dwordx4 v[210:213], v214, s[16:17] offset:528
	s_waitcnt vmcnt(8)
	v_ffbh_u32_e32 v151, v161
	v_min_u32_e32 v151, 32, v151
	v_lshlrev_b64 v[160:161], v151, v[160:161]
	v_sub_u32_e32 v151, 32, v151
	v_min_u32_e32 v160, 1, v160
	v_or_b32_e32 v160, v161, v160
	v_cvt_f32_u32_e32 v160, v160
	v_ldexp_f32 v160, v160, v151
	v_fmamk_f32 v160, v160, 0x30800000, v159
	v_mul_f32_e32 v161, 0x4b800000, v160
	v_cmp_gt_f32_e32 vcc, s57, v160
	s_nop 1
	v_cndmask_b32_e32 v160, v160, v161, vcc
	v_rsq_f32_e32 v160, v160
	s_nop 0
	v_mul_f32_e32 v161, 0x45800000, v160
	v_cndmask_b32_e32 v217, v160, v161, vcc
	v_mul_f32_e64 v92, v92, -v217
	v_mul_f32_e64 v93, v93, -v217
	v_mul_f32_e64 v94, v94, -v217
	v_mul_f32_e64 v95, v95, -v217
	v_mul_f32_e64 v88, v88, -v217
	v_mul_f32_e64 v89, v89, -v217
	v_mul_f32_e64 v90, v90, -v217
	v_mul_f32_e64 v91, v91, -v217
	v_mul_f32_e64 v84, v84, -v217
	v_mul_f32_e64 v85, v85, -v217
	v_mul_f32_e64 v86, v86, -v217
	v_mul_f32_e64 v87, v87, -v217
	v_mul_f32_e64 v80, v80, -v217
	v_mul_f32_e64 v81, v81, -v217
	v_mul_f32_e64 v82, v82, -v217
	v_mul_f32_e64 v83, v83, -v217
	v_mul_f32_e32 v92, 0x3fb8aa3b, v92
	v_mul_f32_e32 v93, 0x3fb8aa3b, v93
	v_mul_f32_e32 v94, 0x3fb8aa3b, v94
	v_mul_f32_e32 v95, 0x3fb8aa3b, v95
	v_mul_f32_e32 v88, 0x3fb8aa3b, v88
	v_mul_f32_e32 v89, 0x3fb8aa3b, v89
	v_mul_f32_e32 v90, 0x3fb8aa3b, v90
	v_mul_f32_e32 v91, 0x3fb8aa3b, v91
	v_mul_f32_e32 v84, 0x3fb8aa3b, v84
	v_mul_f32_e32 v85, 0x3fb8aa3b, v85
	v_mul_f32_e32 v86, 0x3fb8aa3b, v86
	v_mul_f32_e32 v87, 0x3fb8aa3b, v87
	v_mul_f32_e32 v80, 0x3fb8aa3b, v80
	v_mul_f32_e32 v81, 0x3fb8aa3b, v81
	v_mul_f32_e32 v82, 0x3fb8aa3b, v82
	v_mul_f32_e32 v83, 0x3fb8aa3b, v83
	v_exp_f32_e32 v92, v92
	v_exp_f32_e32 v93, v93
	v_exp_f32_e32 v94, v94
	v_exp_f32_e32 v95, v95
	v_exp_f32_e32 v88, v88
	v_exp_f32_e32 v89, v89
	v_exp_f32_e32 v90, v90
	v_exp_f32_e32 v91, v91
	v_exp_f32_e32 v84, v84
	v_exp_f32_e32 v85, v85
	v_exp_f32_e32 v86, v86
	v_exp_f32_e32 v87, v87
	v_exp_f32_e32 v80, v80
	v_exp_f32_e32 v81, v81
	v_exp_f32_e32 v82, v82
	v_exp_f32_e32 v83, v83
	v_add_f32_e32 v92, 1.0, v92
	v_add_f32_e32 v93, 1.0, v93
	v_add_f32_e32 v94, 1.0, v94
	v_add_f32_e32 v95, 1.0, v95
	v_add_f32_e32 v88, 1.0, v88
	v_add_f32_e32 v89, 1.0, v89
	v_add_f32_e32 v90, 1.0, v90
	v_add_f32_e32 v91, 1.0, v91
	v_add_f32_e32 v84, 1.0, v84
	v_add_f32_e32 v85, 1.0, v85
	v_add_f32_e32 v86, 1.0, v86
	v_add_f32_e32 v87, 1.0, v87
	v_add_f32_e32 v80, 1.0, v80
	v_add_f32_e32 v81, 1.0, v81
	v_add_f32_e32 v82, 1.0, v82
	v_add_f32_e32 v83, 1.0, v83
	v_rcp_f32_e32 v92, v92
	v_rcp_f32_e32 v93, v93
	v_rcp_f32_e32 v94, v94
	v_rcp_f32_e32 v95, v95
	v_rcp_f32_e32 v88, v88
	v_rcp_f32_e32 v89, v89
	v_rcp_f32_e32 v90, v90
	v_rcp_f32_e32 v91, v91
	v_rcp_f32_e32 v84, v84
	v_rcp_f32_e32 v85, v85
	v_rcp_f32_e32 v86, v86
	v_rcp_f32_e32 v87, v87
	v_rcp_f32_e32 v80, v80
	v_rcp_f32_e32 v81, v81
	v_rcp_f32_e32 v82, v82
	v_rcp_f32_e32 v83, v83
	s_nop 0
	v_lshlrev_b32_e32 v151, 16, v162
	v_fma_f32 v92, v92, v151, v170
	v_mul_f32_e32 v175, v92, v92
	v_and_b32_e32 v151, 0xffff0000, v162
	v_fma_f32 v93, v93, v151, v171
	v_fmac_f32_e32 v175, v93, v93
	v_lshlrev_b32_e32 v151, 16, v163
	v_fma_f32 v94, v94, v151, v172
	v_fmac_f32_e32 v175, v94, v94
	v_and_b32_e32 v151, 0xffff0000, v163
	v_fma_f32 v95, v95, v151, v173
	v_fmac_f32_e32 v175, v95, v95
	v_lshlrev_b32_e32 v151, 16, v164
	v_fma_f32 v88, v88, v151, v176
	v_fmac_f32_e32 v175, v88, v88
	v_and_b32_e32 v151, 0xffff0000, v164
	v_fma_f32 v89, v89, v151, v177
	v_fmac_f32_e32 v175, v89, v89
	v_lshlrev_b32_e32 v151, 16, v165
	v_fma_f32 v90, v90, v151, v178
	v_fmac_f32_e32 v175, v90, v90
	v_and_b32_e32 v151, 0xffff0000, v165
	v_fma_f32 v91, v91, v151, v179
	v_fmac_f32_e32 v175, v91, v91
	v_lshlrev_b32_e32 v151, 16, v166
	v_fma_f32 v84, v84, v151, v180
	v_fmac_f32_e32 v175, v84, v84
	v_and_b32_e32 v151, 0xffff0000, v166
	v_fma_f32 v85, v85, v151, v181
	v_fmac_f32_e32 v175, v85, v85
	v_lshlrev_b32_e32 v151, 16, v167
	v_fma_f32 v86, v86, v151, v182
	v_fmac_f32_e32 v175, v86, v86
	v_and_b32_e32 v151, 0xffff0000, v167
	v_fma_f32 v87, v87, v151, v183
	v_fmac_f32_e32 v175, v87, v87
	v_lshlrev_b32_e32 v151, 16, v168
	v_fma_f32 v80, v80, v151, v184
	v_fmac_f32_e32 v175, v80, v80
	v_and_b32_e32 v151, 0xffff0000, v168
	v_fma_f32 v81, v81, v151, v185
	v_fmac_f32_e32 v175, v81, v81
	v_lshlrev_b32_e32 v151, 16, v169
	v_fma_f32 v82, v82, v151, v186
	v_fmac_f32_e32 v175, v82, v82
	v_and_b32_e32 v151, 0xffff0000, v169
	v_fma_f32 v83, v83, v151, v187
	v_fmac_f32_e32 v175, v83, v83
	ds_bpermute_b32 v151, v149, v175
	s_waitcnt lgkmcnt(0)
	v_add_f32_e32 v175, v175, v151
	ds_bpermute_b32 v151, v150, v175
	s_waitcnt lgkmcnt(0)
	v_add_f32_e32 v175, v175, v151
	v_mul_f32_e32 v218, 0x49800000, v175
	v_trunc_f32_e32 v218, v218
	v_mul_f32_e32 v219, 0x2f800000, v218
	v_floor_f32_e32 v219, v219
	v_fmac_f32_e32 v218, 0xcf800000, v219
	v_cvt_u32_f32_e32 v218, v218
	v_cvt_u32_f32_e32 v219, v219
	v_add_u32_e32 v151, 0x100, v148
	s_mov_b64 exec, s[6:7]
	global_atomic_add_x2 v151, v[218:219], s[14:15]
	s_mov_b64 exec, -1
	v_add_u32_e32 v214, 0x80000, v145
	v_add_u32_e32 v215, 0x80000, v147
	v_add_u32_e32 v216, 0x400, v148
	global_load_dwordx2 v[160:161], v216, s[18:19]
	global_load_dwordx4 v[162:165], v215, s[12:13]
	global_load_dwordx4 v[166:169], v215, s[12:13] offset:256
	global_load_dwordx4 v[170:173], v214, s[16:17]
	global_load_dwordx4 v[176:179], v214, s[16:17] offset:16
	global_load_dwordx4 v[180:183], v214, s[16:17] offset:512
	global_load_dwordx4 v[184:187], v214, s[16:17] offset:528
	s_waitcnt vmcnt(8)
	v_ffbh_u32_e32 v151, v189
	v_min_u32_e32 v151, 32, v151
	v_lshlrev_b64 v[188:189], v151, v[188:189]
	v_sub_u32_e32 v151, 32, v151
	v_min_u32_e32 v188, 1, v188
	v_or_b32_e32 v188, v189, v188
	v_cvt_f32_u32_e32 v188, v188
	v_ldexp_f32 v188, v188, v151
	v_fmamk_f32 v188, v188, 0x30800000, v159
	v_mul_f32_e32 v189, 0x4b800000, v188
	v_cmp_gt_f32_e32 vcc, s57, v188
	s_nop 1
	v_cndmask_b32_e32 v188, v188, v189, vcc
	v_rsq_f32_e32 v188, v188
	s_nop 0
	v_mul_f32_e32 v189, 0x45800000, v188
	v_cndmask_b32_e32 v217, v188, v189, vcc
	v_mul_f32_e64 v76, v76, -v217
	v_mul_f32_e64 v77, v77, -v217
	v_mul_f32_e64 v78, v78, -v217
	v_mul_f32_e64 v79, v79, -v217
	v_mul_f32_e64 v72, v72, -v217
	v_mul_f32_e64 v73, v73, -v217
	v_mul_f32_e64 v74, v74, -v217
	v_mul_f32_e64 v75, v75, -v217
	v_mul_f32_e64 v68, v68, -v217
	v_mul_f32_e64 v69, v69, -v217
	v_mul_f32_e64 v70, v70, -v217
	v_mul_f32_e64 v71, v71, -v217
	v_mul_f32_e64 v64, v64, -v217
	v_mul_f32_e64 v65, v65, -v217
	v_mul_f32_e64 v66, v66, -v217
	v_mul_f32_e64 v67, v67, -v217
	v_mul_f32_e32 v76, 0x3fb8aa3b, v76
	v_mul_f32_e32 v77, 0x3fb8aa3b, v77
	v_mul_f32_e32 v78, 0x3fb8aa3b, v78
	v_mul_f32_e32 v79, 0x3fb8aa3b, v79
	v_mul_f32_e32 v72, 0x3fb8aa3b, v72
	v_mul_f32_e32 v73, 0x3fb8aa3b, v73
	v_mul_f32_e32 v74, 0x3fb8aa3b, v74
	v_mul_f32_e32 v75, 0x3fb8aa3b, v75
	v_mul_f32_e32 v68, 0x3fb8aa3b, v68
	v_mul_f32_e32 v69, 0x3fb8aa3b, v69
	v_mul_f32_e32 v70, 0x3fb8aa3b, v70
	v_mul_f32_e32 v71, 0x3fb8aa3b, v71
	v_mul_f32_e32 v64, 0x3fb8aa3b, v64
	v_mul_f32_e32 v65, 0x3fb8aa3b, v65
	v_mul_f32_e32 v66, 0x3fb8aa3b, v66
	v_mul_f32_e32 v67, 0x3fb8aa3b, v67
	v_exp_f32_e32 v76, v76
	v_exp_f32_e32 v77, v77
	v_exp_f32_e32 v78, v78
	v_exp_f32_e32 v79, v79
	v_exp_f32_e32 v72, v72
	v_exp_f32_e32 v73, v73
	v_exp_f32_e32 v74, v74
	v_exp_f32_e32 v75, v75
	v_exp_f32_e32 v68, v68
	v_exp_f32_e32 v69, v69
	v_exp_f32_e32 v70, v70
	v_exp_f32_e32 v71, v71
	v_exp_f32_e32 v64, v64
	v_exp_f32_e32 v65, v65
	v_exp_f32_e32 v66, v66
	v_exp_f32_e32 v67, v67
	v_add_f32_e32 v76, 1.0, v76
	v_add_f32_e32 v77, 1.0, v77
	v_add_f32_e32 v78, 1.0, v78
	v_add_f32_e32 v79, 1.0, v79
	v_add_f32_e32 v72, 1.0, v72
	v_add_f32_e32 v73, 1.0, v73
	v_add_f32_e32 v74, 1.0, v74
	v_add_f32_e32 v75, 1.0, v75
	v_add_f32_e32 v68, 1.0, v68
	v_add_f32_e32 v69, 1.0, v69
	v_add_f32_e32 v70, 1.0, v70
	v_add_f32_e32 v71, 1.0, v71
	v_add_f32_e32 v64, 1.0, v64
	v_add_f32_e32 v65, 1.0, v65
	v_add_f32_e32 v66, 1.0, v66
	v_add_f32_e32 v67, 1.0, v67
	v_rcp_f32_e32 v76, v76
	v_rcp_f32_e32 v77, v77
	v_rcp_f32_e32 v78, v78
	v_rcp_f32_e32 v79, v79
	v_rcp_f32_e32 v72, v72
	v_rcp_f32_e32 v73, v73
	v_rcp_f32_e32 v74, v74
	v_rcp_f32_e32 v75, v75
	v_rcp_f32_e32 v68, v68
	v_rcp_f32_e32 v69, v69
	v_rcp_f32_e32 v70, v70
	v_rcp_f32_e32 v71, v71
	v_rcp_f32_e32 v64, v64
	v_rcp_f32_e32 v65, v65
	v_rcp_f32_e32 v66, v66
	v_rcp_f32_e32 v67, v67
	s_nop 0
	v_lshlrev_b32_e32 v151, 16, v190
	v_fma_f32 v76, v76, v151, v198
	v_mul_f32_e32 v175, v76, v76
	v_and_b32_e32 v151, 0xffff0000, v190
	v_fma_f32 v77, v77, v151, v199
	v_fmac_f32_e32 v175, v77, v77
	v_lshlrev_b32_e32 v151, 16, v191
	v_fma_f32 v78, v78, v151, v200
	v_fmac_f32_e32 v175, v78, v78
	v_and_b32_e32 v151, 0xffff0000, v191
	v_fma_f32 v79, v79, v151, v201
	v_fmac_f32_e32 v175, v79, v79
	v_lshlrev_b32_e32 v151, 16, v192
	v_fma_f32 v72, v72, v151, v202
	v_fmac_f32_e32 v175, v72, v72
	v_and_b32_e32 v151, 0xffff0000, v192
	v_fma_f32 v73, v73, v151, v203
	v_fmac_f32_e32 v175, v73, v73
	v_lshlrev_b32_e32 v151, 16, v193
	v_fma_f32 v74, v74, v151, v204
	v_fmac_f32_e32 v175, v74, v74
	v_and_b32_e32 v151, 0xffff0000, v193
	v_fma_f32 v75, v75, v151, v205
	v_fmac_f32_e32 v175, v75, v75
	v_lshlrev_b32_e32 v151, 16, v194
	v_fma_f32 v68, v68, v151, v206
	v_fmac_f32_e32 v175, v68, v68
	v_and_b32_e32 v151, 0xffff0000, v194
	v_fma_f32 v69, v69, v151, v207
	v_fmac_f32_e32 v175, v69, v69
	v_lshlrev_b32_e32 v151, 16, v195
	v_fma_f32 v70, v70, v151, v208
	v_fmac_f32_e32 v175, v70, v70
	v_and_b32_e32 v151, 0xffff0000, v195
	v_fma_f32 v71, v71, v151, v209
	v_fmac_f32_e32 v175, v71, v71
	v_lshlrev_b32_e32 v151, 16, v196
	v_fma_f32 v64, v64, v151, v210
	v_fmac_f32_e32 v175, v64, v64
	v_and_b32_e32 v151, 0xffff0000, v196
	v_fma_f32 v65, v65, v151, v211
	v_fmac_f32_e32 v175, v65, v65
	v_lshlrev_b32_e32 v151, 16, v197
	v_fma_f32 v66, v66, v151, v212
	v_fmac_f32_e32 v175, v66, v66
	v_and_b32_e32 v151, 0xffff0000, v197
	v_fma_f32 v67, v67, v151, v213
	v_fmac_f32_e32 v175, v67, v67
	ds_bpermute_b32 v151, v149, v175
	s_waitcnt lgkmcnt(0)
	v_add_f32_e32 v175, v175, v151
	ds_bpermute_b32 v151, v150, v175
	s_waitcnt lgkmcnt(0)
	v_add_f32_e32 v175, v175, v151
	v_mul_f32_e32 v218, 0x49800000, v175
	v_trunc_f32_e32 v218, v218
	v_mul_f32_e32 v219, 0x2f800000, v218
	v_floor_f32_e32 v219, v219
	v_fmac_f32_e32 v218, 0xcf800000, v219
	v_cvt_u32_f32_e32 v218, v218
	v_cvt_u32_f32_e32 v219, v219
	v_add_u32_e32 v151, 0x180, v148
	s_mov_b64 exec, s[6:7]
	global_atomic_add_x2 v151, v[218:219], s[14:15]
	s_mov_b64 exec, -1
	v_add_u32_e32 v214, 0x90000, v145
	v_add_u32_e32 v215, 0x90000, v147
	v_add_u32_e32 v216, 0x480, v148
	global_load_dwordx2 v[188:189], v216, s[18:19]
	global_load_dwordx4 v[190:193], v215, s[12:13]
	global_load_dwordx4 v[194:197], v215, s[12:13] offset:256
	global_load_dwordx4 v[198:201], v214, s[16:17]
	global_load_dwordx4 v[202:205], v214, s[16:17] offset:16
	global_load_dwordx4 v[206:209], v214, s[16:17] offset:512
	global_load_dwordx4 v[210:213], v214, s[16:17] offset:528
	s_waitcnt vmcnt(8)
	v_ffbh_u32_e32 v151, v161
	v_min_u32_e32 v151, 32, v151
	v_lshlrev_b64 v[160:161], v151, v[160:161]
	v_sub_u32_e32 v151, 32, v151
	v_min_u32_e32 v160, 1, v160
	v_or_b32_e32 v160, v161, v160
	v_cvt_f32_u32_e32 v160, v160
	v_ldexp_f32 v160, v160, v151
	v_fmamk_f32 v160, v160, 0x30800000, v159
	v_mul_f32_e32 v161, 0x4b800000, v160
	v_cmp_gt_f32_e32 vcc, s57, v160
	s_nop 1
	v_cndmask_b32_e32 v160, v160, v161, vcc
	v_rsq_f32_e32 v160, v160
	s_nop 0
	v_mul_f32_e32 v161, 0x45800000, v160
	v_cndmask_b32_e32 v217, v160, v161, vcc
	v_mul_f32_e64 v60, v60, -v217
	v_mul_f32_e64 v61, v61, -v217
	v_mul_f32_e64 v62, v62, -v217
	v_mul_f32_e64 v63, v63, -v217
	v_mul_f32_e64 v56, v56, -v217
	v_mul_f32_e64 v57, v57, -v217
	v_mul_f32_e64 v58, v58, -v217
	v_mul_f32_e64 v59, v59, -v217
	v_mul_f32_e64 v52, v52, -v217
	v_mul_f32_e64 v53, v53, -v217
	v_mul_f32_e64 v54, v54, -v217
	v_mul_f32_e64 v55, v55, -v217
	v_mul_f32_e64 v48, v48, -v217
	v_mul_f32_e64 v49, v49, -v217
	v_mul_f32_e64 v50, v50, -v217
	v_mul_f32_e64 v51, v51, -v217
	v_mul_f32_e32 v60, 0x3fb8aa3b, v60
	v_mul_f32_e32 v61, 0x3fb8aa3b, v61
	v_mul_f32_e32 v62, 0x3fb8aa3b, v62
	v_mul_f32_e32 v63, 0x3fb8aa3b, v63
	v_mul_f32_e32 v56, 0x3fb8aa3b, v56
	v_mul_f32_e32 v57, 0x3fb8aa3b, v57
	v_mul_f32_e32 v58, 0x3fb8aa3b, v58
	v_mul_f32_e32 v59, 0x3fb8aa3b, v59
	v_mul_f32_e32 v52, 0x3fb8aa3b, v52
	v_mul_f32_e32 v53, 0x3fb8aa3b, v53
	v_mul_f32_e32 v54, 0x3fb8aa3b, v54
	v_mul_f32_e32 v55, 0x3fb8aa3b, v55
	v_mul_f32_e32 v48, 0x3fb8aa3b, v48
	v_mul_f32_e32 v49, 0x3fb8aa3b, v49
	v_mul_f32_e32 v50, 0x3fb8aa3b, v50
	v_mul_f32_e32 v51, 0x3fb8aa3b, v51
	v_exp_f32_e32 v60, v60
	v_exp_f32_e32 v61, v61
	v_exp_f32_e32 v62, v62
	v_exp_f32_e32 v63, v63
	v_exp_f32_e32 v56, v56
	v_exp_f32_e32 v57, v57
	v_exp_f32_e32 v58, v58
	v_exp_f32_e32 v59, v59
	v_exp_f32_e32 v52, v52
	v_exp_f32_e32 v53, v53
	v_exp_f32_e32 v54, v54
	v_exp_f32_e32 v55, v55
	v_exp_f32_e32 v48, v48
	v_exp_f32_e32 v49, v49
	v_exp_f32_e32 v50, v50
	v_exp_f32_e32 v51, v51
	v_add_f32_e32 v60, 1.0, v60
	v_add_f32_e32 v61, 1.0, v61
	v_add_f32_e32 v62, 1.0, v62
	v_add_f32_e32 v63, 1.0, v63
	v_add_f32_e32 v56, 1.0, v56
	v_add_f32_e32 v57, 1.0, v57
	v_add_f32_e32 v58, 1.0, v58
	v_add_f32_e32 v59, 1.0, v59
	v_add_f32_e32 v52, 1.0, v52
	v_add_f32_e32 v53, 1.0, v53
	v_add_f32_e32 v54, 1.0, v54
	v_add_f32_e32 v55, 1.0, v55
	v_add_f32_e32 v48, 1.0, v48
	v_add_f32_e32 v49, 1.0, v49
	v_add_f32_e32 v50, 1.0, v50
	v_add_f32_e32 v51, 1.0, v51
	v_rcp_f32_e32 v60, v60
	v_rcp_f32_e32 v61, v61
	v_rcp_f32_e32 v62, v62
	v_rcp_f32_e32 v63, v63
	v_rcp_f32_e32 v56, v56
	v_rcp_f32_e32 v57, v57
	v_rcp_f32_e32 v58, v58
	v_rcp_f32_e32 v59, v59
	v_rcp_f32_e32 v52, v52
	v_rcp_f32_e32 v53, v53
	v_rcp_f32_e32 v54, v54
	v_rcp_f32_e32 v55, v55
	v_rcp_f32_e32 v48, v48
	v_rcp_f32_e32 v49, v49
	v_rcp_f32_e32 v50, v50
	v_rcp_f32_e32 v51, v51
	s_nop 0
	v_lshlrev_b32_e32 v151, 16, v162
	v_fma_f32 v60, v60, v151, v170
	v_mul_f32_e32 v175, v60, v60
	v_and_b32_e32 v151, 0xffff0000, v162
	v_fma_f32 v61, v61, v151, v171
	v_fmac_f32_e32 v175, v61, v61
	v_lshlrev_b32_e32 v151, 16, v163
	v_fma_f32 v62, v62, v151, v172
	v_fmac_f32_e32 v175, v62, v62
	v_and_b32_e32 v151, 0xffff0000, v163
	v_fma_f32 v63, v63, v151, v173
	v_fmac_f32_e32 v175, v63, v63
	v_lshlrev_b32_e32 v151, 16, v164
	v_fma_f32 v56, v56, v151, v176
	v_fmac_f32_e32 v175, v56, v56
	v_and_b32_e32 v151, 0xffff0000, v164
	v_fma_f32 v57, v57, v151, v177
	v_fmac_f32_e32 v175, v57, v57
	v_lshlrev_b32_e32 v151, 16, v165
	v_fma_f32 v58, v58, v151, v178
	v_fmac_f32_e32 v175, v58, v58
	v_and_b32_e32 v151, 0xffff0000, v165
	v_fma_f32 v59, v59, v151, v179
	v_fmac_f32_e32 v175, v59, v59
	v_lshlrev_b32_e32 v151, 16, v166
	v_fma_f32 v52, v52, v151, v180
	v_fmac_f32_e32 v175, v52, v52
	v_and_b32_e32 v151, 0xffff0000, v166
	v_fma_f32 v53, v53, v151, v181
	v_fmac_f32_e32 v175, v53, v53
	v_lshlrev_b32_e32 v151, 16, v167
	v_fma_f32 v54, v54, v151, v182
	v_fmac_f32_e32 v175, v54, v54
	v_and_b32_e32 v151, 0xffff0000, v167
	v_fma_f32 v55, v55, v151, v183
	v_fmac_f32_e32 v175, v55, v55
	v_lshlrev_b32_e32 v151, 16, v168
	v_fma_f32 v48, v48, v151, v184
	v_fmac_f32_e32 v175, v48, v48
	v_and_b32_e32 v151, 0xffff0000, v168
	v_fma_f32 v49, v49, v151, v185
	v_fmac_f32_e32 v175, v49, v49
	v_lshlrev_b32_e32 v151, 16, v169
	v_fma_f32 v50, v50, v151, v186
	v_fmac_f32_e32 v175, v50, v50
	v_and_b32_e32 v151, 0xffff0000, v169
	v_fma_f32 v51, v51, v151, v187
	v_fmac_f32_e32 v175, v51, v51
	ds_bpermute_b32 v151, v149, v175
	s_waitcnt lgkmcnt(0)
	v_add_f32_e32 v175, v175, v151
	ds_bpermute_b32 v151, v150, v175
	s_waitcnt lgkmcnt(0)
	v_add_f32_e32 v175, v175, v151
	v_mul_f32_e32 v218, 0x49800000, v175
	v_trunc_f32_e32 v218, v218
	v_mul_f32_e32 v219, 0x2f800000, v218
	v_floor_f32_e32 v219, v219
	v_fmac_f32_e32 v218, 0xcf800000, v219
	v_cvt_u32_f32_e32 v218, v218
	v_cvt_u32_f32_e32 v219, v219
	v_add_u32_e32 v151, 0x400, v148
	s_mov_b64 exec, s[6:7]
	global_atomic_add_x2 v151, v[218:219], s[14:15]
	s_mov_b64 exec, -1
	v_add_u32_e32 v214, 0xa0000, v145
	v_add_u32_e32 v215, 0xa0000, v147
	v_add_u32_e32 v216, 0x500, v148
	global_load_dwordx2 v[160:161], v216, s[18:19]
	global_load_dwordx4 v[162:165], v215, s[12:13]
	global_load_dwordx4 v[166:169], v215, s[12:13] offset:256
	global_load_dwordx4 v[170:173], v214, s[16:17]
	global_load_dwordx4 v[176:179], v214, s[16:17] offset:16
	global_load_dwordx4 v[180:183], v214, s[16:17] offset:512
	global_load_dwordx4 v[184:187], v214, s[16:17] offset:528
	s_waitcnt vmcnt(8)
	v_ffbh_u32_e32 v151, v189
	v_min_u32_e32 v151, 32, v151
	v_lshlrev_b64 v[188:189], v151, v[188:189]
	v_sub_u32_e32 v151, 32, v151
	v_min_u32_e32 v188, 1, v188
	v_or_b32_e32 v188, v189, v188
	v_cvt_f32_u32_e32 v188, v188
	v_ldexp_f32 v188, v188, v151
	v_fmamk_f32 v188, v188, 0x30800000, v159
	v_mul_f32_e32 v189, 0x4b800000, v188
	v_cmp_gt_f32_e32 vcc, s57, v188
	s_nop 1
	v_cndmask_b32_e32 v188, v188, v189, vcc
	v_rsq_f32_e32 v188, v188
	s_nop 0
	v_mul_f32_e32 v189, 0x45800000, v188
	v_cndmask_b32_e32 v217, v188, v189, vcc
	v_mul_f32_e64 v44, v44, -v217
	v_mul_f32_e64 v45, v45, -v217
	v_mul_f32_e64 v46, v46, -v217
	v_mul_f32_e64 v47, v47, -v217
	v_mul_f32_e64 v40, v40, -v217
	v_mul_f32_e64 v41, v41, -v217
	v_mul_f32_e64 v42, v42, -v217
	v_mul_f32_e64 v43, v43, -v217
	v_mul_f32_e64 v36, v36, -v217
	v_mul_f32_e64 v37, v37, -v217
	v_mul_f32_e64 v38, v38, -v217
	v_mul_f32_e64 v39, v39, -v217
	v_mul_f32_e64 v32, v32, -v217
	v_mul_f32_e64 v33, v33, -v217
	v_mul_f32_e64 v34, v34, -v217
	v_mul_f32_e64 v35, v35, -v217
	v_mul_f32_e32 v44, 0x3fb8aa3b, v44
	v_mul_f32_e32 v45, 0x3fb8aa3b, v45
	v_mul_f32_e32 v46, 0x3fb8aa3b, v46
	v_mul_f32_e32 v47, 0x3fb8aa3b, v47
	v_mul_f32_e32 v40, 0x3fb8aa3b, v40
	v_mul_f32_e32 v41, 0x3fb8aa3b, v41
	v_mul_f32_e32 v42, 0x3fb8aa3b, v42
	v_mul_f32_e32 v43, 0x3fb8aa3b, v43
	v_mul_f32_e32 v36, 0x3fb8aa3b, v36
	v_mul_f32_e32 v37, 0x3fb8aa3b, v37
	v_mul_f32_e32 v38, 0x3fb8aa3b, v38
	v_mul_f32_e32 v39, 0x3fb8aa3b, v39
	v_mul_f32_e32 v32, 0x3fb8aa3b, v32
	v_mul_f32_e32 v33, 0x3fb8aa3b, v33
	v_mul_f32_e32 v34, 0x3fb8aa3b, v34
	v_mul_f32_e32 v35, 0x3fb8aa3b, v35
	v_exp_f32_e32 v44, v44
	v_exp_f32_e32 v45, v45
	v_exp_f32_e32 v46, v46
	v_exp_f32_e32 v47, v47
	v_exp_f32_e32 v40, v40
	v_exp_f32_e32 v41, v41
	v_exp_f32_e32 v42, v42
	v_exp_f32_e32 v43, v43
	v_exp_f32_e32 v36, v36
	v_exp_f32_e32 v37, v37
	v_exp_f32_e32 v38, v38
	v_exp_f32_e32 v39, v39
	v_exp_f32_e32 v32, v32
	v_exp_f32_e32 v33, v33
	v_exp_f32_e32 v34, v34
	v_exp_f32_e32 v35, v35
	v_add_f32_e32 v44, 1.0, v44
	v_add_f32_e32 v45, 1.0, v45
	v_add_f32_e32 v46, 1.0, v46
	v_add_f32_e32 v47, 1.0, v47
	v_add_f32_e32 v40, 1.0, v40
	v_add_f32_e32 v41, 1.0, v41
	v_add_f32_e32 v42, 1.0, v42
	v_add_f32_e32 v43, 1.0, v43
	v_add_f32_e32 v36, 1.0, v36
	v_add_f32_e32 v37, 1.0, v37
	v_add_f32_e32 v38, 1.0, v38
	v_add_f32_e32 v39, 1.0, v39
	v_add_f32_e32 v32, 1.0, v32
	v_add_f32_e32 v33, 1.0, v33
	v_add_f32_e32 v34, 1.0, v34
	v_add_f32_e32 v35, 1.0, v35
	v_rcp_f32_e32 v44, v44
	v_rcp_f32_e32 v45, v45
	v_rcp_f32_e32 v46, v46
	v_rcp_f32_e32 v47, v47
	v_rcp_f32_e32 v40, v40
	v_rcp_f32_e32 v41, v41
	v_rcp_f32_e32 v42, v42
	v_rcp_f32_e32 v43, v43
	v_rcp_f32_e32 v36, v36
	v_rcp_f32_e32 v37, v37
	v_rcp_f32_e32 v38, v38
	v_rcp_f32_e32 v39, v39
	v_rcp_f32_e32 v32, v32
	v_rcp_f32_e32 v33, v33
	v_rcp_f32_e32 v34, v34
	v_rcp_f32_e32 v35, v35
	s_nop 0
	v_lshlrev_b32_e32 v151, 16, v190
	v_fma_f32 v44, v44, v151, v198
	v_mul_f32_e32 v175, v44, v44
	v_and_b32_e32 v151, 0xffff0000, v190
	v_fma_f32 v45, v45, v151, v199
	v_fmac_f32_e32 v175, v45, v45
	v_lshlrev_b32_e32 v151, 16, v191
	v_fma_f32 v46, v46, v151, v200
	v_fmac_f32_e32 v175, v46, v46
	v_and_b32_e32 v151, 0xffff0000, v191
	v_fma_f32 v47, v47, v151, v201
	v_fmac_f32_e32 v175, v47, v47
	v_lshlrev_b32_e32 v151, 16, v192
	v_fma_f32 v40, v40, v151, v202
	v_fmac_f32_e32 v175, v40, v40
	v_and_b32_e32 v151, 0xffff0000, v192
	v_fma_f32 v41, v41, v151, v203
	v_fmac_f32_e32 v175, v41, v41
	v_lshlrev_b32_e32 v151, 16, v193
	v_fma_f32 v42, v42, v151, v204
	v_fmac_f32_e32 v175, v42, v42
	v_and_b32_e32 v151, 0xffff0000, v193
	v_fma_f32 v43, v43, v151, v205
	v_fmac_f32_e32 v175, v43, v43
	v_lshlrev_b32_e32 v151, 16, v194
	v_fma_f32 v36, v36, v151, v206
	v_fmac_f32_e32 v175, v36, v36
	v_and_b32_e32 v151, 0xffff0000, v194
	v_fma_f32 v37, v37, v151, v207
	v_fmac_f32_e32 v175, v37, v37
	v_lshlrev_b32_e32 v151, 16, v195
	v_fma_f32 v38, v38, v151, v208
	v_fmac_f32_e32 v175, v38, v38
	v_and_b32_e32 v151, 0xffff0000, v195
	v_fma_f32 v39, v39, v151, v209
	v_fmac_f32_e32 v175, v39, v39
	v_lshlrev_b32_e32 v151, 16, v196
	v_fma_f32 v32, v32, v151, v210
	v_fmac_f32_e32 v175, v32, v32
	v_and_b32_e32 v151, 0xffff0000, v196
	v_fma_f32 v33, v33, v151, v211
	v_fmac_f32_e32 v175, v33, v33
	v_lshlrev_b32_e32 v151, 16, v197
	v_fma_f32 v34, v34, v151, v212
	v_fmac_f32_e32 v175, v34, v34
	v_and_b32_e32 v151, 0xffff0000, v197
	v_fma_f32 v35, v35, v151, v213
	v_fmac_f32_e32 v175, v35, v35
	ds_bpermute_b32 v151, v149, v175
	s_waitcnt lgkmcnt(0)
	v_add_f32_e32 v175, v175, v151
	ds_bpermute_b32 v151, v150, v175
	s_waitcnt lgkmcnt(0)
	v_add_f32_e32 v175, v175, v151
	v_mul_f32_e32 v218, 0x49800000, v175
	v_trunc_f32_e32 v218, v218
	v_mul_f32_e32 v219, 0x2f800000, v218
	v_floor_f32_e32 v219, v219
	v_fmac_f32_e32 v218, 0xcf800000, v219
	v_cvt_u32_f32_e32 v218, v218
	v_cvt_u32_f32_e32 v219, v219
	v_add_u32_e32 v151, 0x480, v148
	s_mov_b64 exec, s[6:7]
	global_atomic_add_x2 v151, v[218:219], s[14:15]
	s_mov_b64 exec, -1
	v_add_u32_e32 v214, 0xb0000, v145
	v_add_u32_e32 v215, 0xb0000, v147
	v_add_u32_e32 v216, 0x580, v148
	global_load_dwordx2 v[188:189], v216, s[18:19]
	global_load_dwordx4 v[190:193], v215, s[12:13]
	global_load_dwordx4 v[194:197], v215, s[12:13] offset:256
	global_load_dwordx4 v[198:201], v214, s[16:17]
	global_load_dwordx4 v[202:205], v214, s[16:17] offset:16
	global_load_dwordx4 v[206:209], v214, s[16:17] offset:512
	global_load_dwordx4 v[210:213], v214, s[16:17] offset:528
	s_waitcnt vmcnt(8)
	v_ffbh_u32_e32 v151, v161
	v_min_u32_e32 v151, 32, v151
	v_lshlrev_b64 v[160:161], v151, v[160:161]
	v_sub_u32_e32 v151, 32, v151
	v_min_u32_e32 v160, 1, v160
	v_or_b32_e32 v160, v161, v160
	v_cvt_f32_u32_e32 v160, v160
	v_ldexp_f32 v160, v160, v151
	v_fmamk_f32 v160, v160, 0x30800000, v159
	v_mul_f32_e32 v161, 0x4b800000, v160
	v_cmp_gt_f32_e32 vcc, s57, v160
	s_nop 1
	v_cndmask_b32_e32 v160, v160, v161, vcc
	v_rsq_f32_e32 v160, v160
	s_nop 0
	v_mul_f32_e32 v161, 0x45800000, v160
	v_cndmask_b32_e32 v217, v160, v161, vcc
	v_mul_f32_e64 v28, v28, -v217
	v_mul_f32_e64 v29, v29, -v217
	v_mul_f32_e64 v30, v30, -v217
	v_mul_f32_e64 v31, v31, -v217
	v_mul_f32_e64 v24, v24, -v217
	v_mul_f32_e64 v25, v25, -v217
	v_mul_f32_e64 v26, v26, -v217
	v_mul_f32_e64 v27, v27, -v217
	v_mul_f32_e64 v20, v20, -v217
	v_mul_f32_e64 v21, v21, -v217
	v_mul_f32_e64 v22, v22, -v217
	v_mul_f32_e64 v23, v23, -v217
	v_mul_f32_e64 v16, v16, -v217
	v_mul_f32_e64 v17, v17, -v217
	v_mul_f32_e64 v18, v18, -v217
	v_mul_f32_e64 v19, v19, -v217
	v_mul_f32_e32 v28, 0x3fb8aa3b, v28
	v_mul_f32_e32 v29, 0x3fb8aa3b, v29
	v_mul_f32_e32 v30, 0x3fb8aa3b, v30
	v_mul_f32_e32 v31, 0x3fb8aa3b, v31
	v_mul_f32_e32 v24, 0x3fb8aa3b, v24
	v_mul_f32_e32 v25, 0x3fb8aa3b, v25
	v_mul_f32_e32 v26, 0x3fb8aa3b, v26
	v_mul_f32_e32 v27, 0x3fb8aa3b, v27
	v_mul_f32_e32 v20, 0x3fb8aa3b, v20
	v_mul_f32_e32 v21, 0x3fb8aa3b, v21
	v_mul_f32_e32 v22, 0x3fb8aa3b, v22
	v_mul_f32_e32 v23, 0x3fb8aa3b, v23
	v_mul_f32_e32 v16, 0x3fb8aa3b, v16
	v_mul_f32_e32 v17, 0x3fb8aa3b, v17
	v_mul_f32_e32 v18, 0x3fb8aa3b, v18
	v_mul_f32_e32 v19, 0x3fb8aa3b, v19
	v_exp_f32_e32 v28, v28
	v_exp_f32_e32 v29, v29
	v_exp_f32_e32 v30, v30
	v_exp_f32_e32 v31, v31
	v_exp_f32_e32 v24, v24
	v_exp_f32_e32 v25, v25
	v_exp_f32_e32 v26, v26
	v_exp_f32_e32 v27, v27
	v_exp_f32_e32 v20, v20
	v_exp_f32_e32 v21, v21
	v_exp_f32_e32 v22, v22
	v_exp_f32_e32 v23, v23
	v_exp_f32_e32 v16, v16
	v_exp_f32_e32 v17, v17
	v_exp_f32_e32 v18, v18
	v_exp_f32_e32 v19, v19
	v_add_f32_e32 v28, 1.0, v28
	v_add_f32_e32 v29, 1.0, v29
	v_add_f32_e32 v30, 1.0, v30
	v_add_f32_e32 v31, 1.0, v31
	v_add_f32_e32 v24, 1.0, v24
	v_add_f32_e32 v25, 1.0, v25
	v_add_f32_e32 v26, 1.0, v26
	v_add_f32_e32 v27, 1.0, v27
	v_add_f32_e32 v20, 1.0, v20
	v_add_f32_e32 v21, 1.0, v21
	v_add_f32_e32 v22, 1.0, v22
	v_add_f32_e32 v23, 1.0, v23
	v_add_f32_e32 v16, 1.0, v16
	v_add_f32_e32 v17, 1.0, v17
	v_add_f32_e32 v18, 1.0, v18
	v_add_f32_e32 v19, 1.0, v19
	v_rcp_f32_e32 v28, v28
	v_rcp_f32_e32 v29, v29
	v_rcp_f32_e32 v30, v30
	v_rcp_f32_e32 v31, v31
	v_rcp_f32_e32 v24, v24
	v_rcp_f32_e32 v25, v25
	v_rcp_f32_e32 v26, v26
	v_rcp_f32_e32 v27, v27
	v_rcp_f32_e32 v20, v20
	v_rcp_f32_e32 v21, v21
	v_rcp_f32_e32 v22, v22
	v_rcp_f32_e32 v23, v23
	v_rcp_f32_e32 v16, v16
	v_rcp_f32_e32 v17, v17
	v_rcp_f32_e32 v18, v18
	v_rcp_f32_e32 v19, v19
	s_nop 0
	v_lshlrev_b32_e32 v151, 16, v162
	v_fma_f32 v28, v28, v151, v170
	v_mul_f32_e32 v175, v28, v28
	v_and_b32_e32 v151, 0xffff0000, v162
	v_fma_f32 v29, v29, v151, v171
	v_fmac_f32_e32 v175, v29, v29
	v_lshlrev_b32_e32 v151, 16, v163
	v_fma_f32 v30, v30, v151, v172
	v_fmac_f32_e32 v175, v30, v30
	v_and_b32_e32 v151, 0xffff0000, v163
	v_fma_f32 v31, v31, v151, v173
	v_fmac_f32_e32 v175, v31, v31
	v_lshlrev_b32_e32 v151, 16, v164
	v_fma_f32 v24, v24, v151, v176
	v_fmac_f32_e32 v175, v24, v24
	v_and_b32_e32 v151, 0xffff0000, v164
	v_fma_f32 v25, v25, v151, v177
	v_fmac_f32_e32 v175, v25, v25
	v_lshlrev_b32_e32 v151, 16, v165
	v_fma_f32 v26, v26, v151, v178
	v_fmac_f32_e32 v175, v26, v26
	v_and_b32_e32 v151, 0xffff0000, v165
	v_fma_f32 v27, v27, v151, v179
	v_fmac_f32_e32 v175, v27, v27
	v_lshlrev_b32_e32 v151, 16, v166
	v_fma_f32 v20, v20, v151, v180
	v_fmac_f32_e32 v175, v20, v20
	v_and_b32_e32 v151, 0xffff0000, v166
	v_fma_f32 v21, v21, v151, v181
	v_fmac_f32_e32 v175, v21, v21
	v_lshlrev_b32_e32 v151, 16, v167
	v_fma_f32 v22, v22, v151, v182
	v_fmac_f32_e32 v175, v22, v22
	v_and_b32_e32 v151, 0xffff0000, v167
	v_fma_f32 v23, v23, v151, v183
	v_fmac_f32_e32 v175, v23, v23
	v_lshlrev_b32_e32 v151, 16, v168
	v_fma_f32 v16, v16, v151, v184
	v_fmac_f32_e32 v175, v16, v16
	v_and_b32_e32 v151, 0xffff0000, v168
	v_fma_f32 v17, v17, v151, v185
	v_fmac_f32_e32 v175, v17, v17
	v_lshlrev_b32_e32 v151, 16, v169
	v_fma_f32 v18, v18, v151, v186
	v_fmac_f32_e32 v175, v18, v18
	v_and_b32_e32 v151, 0xffff0000, v169
	v_fma_f32 v19, v19, v151, v187
	v_fmac_f32_e32 v175, v19, v19
	ds_bpermute_b32 v151, v149, v175
	s_waitcnt lgkmcnt(0)
	v_add_f32_e32 v175, v175, v151
	ds_bpermute_b32 v151, v150, v175
	s_waitcnt lgkmcnt(0)
	v_add_f32_e32 v175, v175, v151
	v_mul_f32_e32 v218, 0x49800000, v175
	v_trunc_f32_e32 v218, v218
	v_mul_f32_e32 v219, 0x2f800000, v218
	v_floor_f32_e32 v219, v219
	v_fmac_f32_e32 v218, 0xcf800000, v219
	v_cvt_u32_f32_e32 v218, v218
	v_cvt_u32_f32_e32 v219, v219
	v_add_u32_e32 v151, 0x500, v148
	s_mov_b64 exec, s[6:7]
	global_atomic_add_x2 v151, v[218:219], s[14:15]
	s_mov_b64 exec, -1
	s_waitcnt vmcnt(1)
	v_ffbh_u32_e32 v151, v189
	v_min_u32_e32 v151, 32, v151
	v_lshlrev_b64 v[188:189], v151, v[188:189]
	v_sub_u32_e32 v151, 32, v151
	v_min_u32_e32 v188, 1, v188
	v_or_b32_e32 v188, v189, v188
	v_cvt_f32_u32_e32 v188, v188
	v_ldexp_f32 v188, v188, v151
	v_fmamk_f32 v188, v188, 0x30800000, v159
	v_mul_f32_e32 v189, 0x4b800000, v188
	v_cmp_gt_f32_e32 vcc, s57, v188
	s_nop 1
	v_cndmask_b32_e32 v188, v188, v189, vcc
	v_rsq_f32_e32 v188, v188
	s_nop 0
	v_mul_f32_e32 v189, 0x45800000, v188
	v_cndmask_b32_e32 v217, v188, v189, vcc
	v_mul_f32_e64 v12, v12, -v217
	v_mul_f32_e64 v13, v13, -v217
	v_mul_f32_e64 v14, v14, -v217
	v_mul_f32_e64 v15, v15, -v217
	v_mul_f32_e64 v8, v8, -v217
	v_mul_f32_e64 v9, v9, -v217
	v_mul_f32_e64 v10, v10, -v217
	v_mul_f32_e64 v11, v11, -v217
	v_mul_f32_e64 v4, v4, -v217
	v_mul_f32_e64 v5, v5, -v217
	v_mul_f32_e64 v6, v6, -v217
	v_mul_f32_e64 v7, v7, -v217
	v_mul_f32_e64 v0, v0, -v217
	v_mul_f32_e64 v1, v1, -v217
	v_mul_f32_e64 v2, v2, -v217
	v_mul_f32_e64 v3, v3, -v217
	v_mul_f32_e32 v12, 0x3fb8aa3b, v12
	v_mul_f32_e32 v13, 0x3fb8aa3b, v13
	v_mul_f32_e32 v14, 0x3fb8aa3b, v14
	v_mul_f32_e32 v15, 0x3fb8aa3b, v15
	v_mul_f32_e32 v8, 0x3fb8aa3b, v8
	v_mul_f32_e32 v9, 0x3fb8aa3b, v9
	v_mul_f32_e32 v10, 0x3fb8aa3b, v10
	v_mul_f32_e32 v11, 0x3fb8aa3b, v11
	v_mul_f32_e32 v4, 0x3fb8aa3b, v4
	v_mul_f32_e32 v5, 0x3fb8aa3b, v5
	v_mul_f32_e32 v6, 0x3fb8aa3b, v6
	v_mul_f32_e32 v7, 0x3fb8aa3b, v7
	v_mul_f32_e32 v0, 0x3fb8aa3b, v0
	v_mul_f32_e32 v1, 0x3fb8aa3b, v1
	v_mul_f32_e32 v2, 0x3fb8aa3b, v2
	v_mul_f32_e32 v3, 0x3fb8aa3b, v3
	v_exp_f32_e32 v12, v12
	v_exp_f32_e32 v13, v13
	v_exp_f32_e32 v14, v14
	v_exp_f32_e32 v15, v15
	v_exp_f32_e32 v8, v8
	v_exp_f32_e32 v9, v9
	v_exp_f32_e32 v10, v10
	v_exp_f32_e32 v11, v11
	v_exp_f32_e32 v4, v4
	v_exp_f32_e32 v5, v5
	v_exp_f32_e32 v6, v6
	v_exp_f32_e32 v7, v7
	v_exp_f32_e32 v0, v0
	v_exp_f32_e32 v1, v1
	v_exp_f32_e32 v2, v2
	v_exp_f32_e32 v3, v3
	v_add_f32_e32 v12, 1.0, v12
	v_add_f32_e32 v13, 1.0, v13
	v_add_f32_e32 v14, 1.0, v14
	v_add_f32_e32 v15, 1.0, v15
	v_add_f32_e32 v8, 1.0, v8
	v_add_f32_e32 v9, 1.0, v9
	v_add_f32_e32 v10, 1.0, v10
	v_add_f32_e32 v11, 1.0, v11
	v_add_f32_e32 v4, 1.0, v4
	v_add_f32_e32 v5, 1.0, v5
	v_add_f32_e32 v6, 1.0, v6
	v_add_f32_e32 v7, 1.0, v7
	v_add_f32_e32 v0, 1.0, v0
	v_add_f32_e32 v1, 1.0, v1
	v_add_f32_e32 v2, 1.0, v2
	v_add_f32_e32 v3, 1.0, v3
	v_rcp_f32_e32 v12, v12
	v_rcp_f32_e32 v13, v13
	v_rcp_f32_e32 v14, v14
	v_rcp_f32_e32 v15, v15
	v_rcp_f32_e32 v8, v8
	v_rcp_f32_e32 v9, v9
	v_rcp_f32_e32 v10, v10
	v_rcp_f32_e32 v11, v11
	v_rcp_f32_e32 v4, v4
	v_rcp_f32_e32 v5, v5
	v_rcp_f32_e32 v6, v6
	v_rcp_f32_e32 v7, v7
	v_rcp_f32_e32 v0, v0
	v_rcp_f32_e32 v1, v1
	v_rcp_f32_e32 v2, v2
	v_rcp_f32_e32 v3, v3
	s_nop 0
	v_lshlrev_b32_e32 v151, 16, v190
	v_fma_f32 v12, v12, v151, v198
	v_mul_f32_e32 v175, v12, v12
	v_and_b32_e32 v151, 0xffff0000, v190
	v_fma_f32 v13, v13, v151, v199
	v_fmac_f32_e32 v175, v13, v13
	v_lshlrev_b32_e32 v151, 16, v191
	v_fma_f32 v14, v14, v151, v200
	v_fmac_f32_e32 v175, v14, v14
	v_and_b32_e32 v151, 0xffff0000, v191
	v_fma_f32 v15, v15, v151, v201
	v_fmac_f32_e32 v175, v15, v15
	v_lshlrev_b32_e32 v151, 16, v192
	v_fma_f32 v8, v8, v151, v202
	v_fmac_f32_e32 v175, v8, v8
	v_and_b32_e32 v151, 0xffff0000, v192
	v_fma_f32 v9, v9, v151, v203
	v_fmac_f32_e32 v175, v9, v9
	v_lshlrev_b32_e32 v151, 16, v193
	v_fma_f32 v10, v10, v151, v204
	v_fmac_f32_e32 v175, v10, v10
	v_and_b32_e32 v151, 0xffff0000, v193
	v_fma_f32 v11, v11, v151, v205
	v_fmac_f32_e32 v175, v11, v11
	v_lshlrev_b32_e32 v151, 16, v194
	v_fma_f32 v4, v4, v151, v206
	v_fmac_f32_e32 v175, v4, v4
	v_and_b32_e32 v151, 0xffff0000, v194
	v_fma_f32 v5, v5, v151, v207
	v_fmac_f32_e32 v175, v5, v5
	v_lshlrev_b32_e32 v151, 16, v195
	v_fma_f32 v6, v6, v151, v208
	v_fmac_f32_e32 v175, v6, v6
	v_and_b32_e32 v151, 0xffff0000, v195
	v_fma_f32 v7, v7, v151, v209
	v_fmac_f32_e32 v175, v7, v7
	v_lshlrev_b32_e32 v151, 16, v196
	v_fma_f32 v0, v0, v151, v210
	v_fmac_f32_e32 v175, v0, v0
	v_and_b32_e32 v151, 0xffff0000, v196
	v_fma_f32 v1, v1, v151, v211
	v_fmac_f32_e32 v175, v1, v1
	v_lshlrev_b32_e32 v151, 16, v197
	v_fma_f32 v2, v2, v151, v212
	v_fmac_f32_e32 v175, v2, v2
	v_and_b32_e32 v151, 0xffff0000, v197
	v_fma_f32 v3, v3, v151, v213
	v_fmac_f32_e32 v175, v3, v3
	ds_bpermute_b32 v151, v149, v175
	s_waitcnt lgkmcnt(0)
	v_add_f32_e32 v175, v175, v151
	ds_bpermute_b32 v151, v150, v175
	s_waitcnt lgkmcnt(0)
	v_add_f32_e32 v175, v175, v151
	v_mul_f32_e32 v218, 0x49800000, v175
	v_trunc_f32_e32 v218, v218
	v_mul_f32_e32 v219, 0x2f800000, v218
	v_floor_f32_e32 v219, v219
	v_fmac_f32_e32 v218, 0xcf800000, v219
	v_cvt_u32_f32_e32 v218, v218
	v_cvt_u32_f32_e32 v219, v219
	v_add_u32_e32 v151, 0x580, v148
	s_mov_b64 exec, s[6:7]
	global_atomic_add_x2 v151, v[218:219], s[14:15]
	s_mov_b64 exec, -1
	s_waitcnt lgkmcnt(0)
	v_lshlrev_b32_e32 v214, 2, v144
	global_load_dwordx4 v[160:163], v214, s[98:99]
	global_load_dwordx4 v[164:167], v214, s[98:99] offset:16
	global_load_dwordx4 v[168:171], v214, s[98:99] offset:512
	global_load_dwordx4 v[176:179], v214, s[98:99] offset:528
	s_lshl_b32 s90, s36, 1
	s_add_u32 s90, s90, s94
	s_lshl_b32 s90, s90, 7
	s_add_u32 s90, s90, 0xe8000
	s_add_u32 s92, s66, s90
	s_addc_u32 s93, s67, 0
	v_mov_b32_e32 v215, 0
	v_mov_b32_e32 v216, 1
	s_waitcnt vmcnt(0)
	s_mov_b64 exec, 1
	global_atomic_add v215, v216, s[92:93]
	s_mov_b64 exec, -1
	s_mov_b32 s91, 0
.Lp6f_spin:
	global_load_dword v151, v215, s[92:93] sc1
	s_waitcnt vmcnt(0)
	v_readfirstlane_b32 s90, v151
	s_cmp_ge_u32 s90, 16
	s_cbranch_scc1 .Lp6f_go
	s_sleep 2
	s_add_u32 s91, s91, 1
	s_cmp_lt_u32 s91, 0x10000
	s_cbranch_scc1 .Lp6f_spin
.Lp6f_go:
	global_load_dwordx2 v[184:185], v148, s[14:15] sc1
	v_add_u32_e32 v151, 0x80, v148
	global_load_dwordx2 v[186:187], v151, s[14:15] sc1
	v_add_u32_e32 v151, 0x100, v148
	global_load_dwordx2 v[188:189], v151, s[14:15] sc1
	v_add_u32_e32 v151, 0x180, v148
	global_load_dwordx2 v[190:191], v151, s[14:15] sc1
	v_add_u32_e32 v151, 0x400, v148
	global_load_dwordx2 v[192:193], v151, s[14:15] sc1
	v_add_u32_e32 v151, 0x480, v148
	global_load_dwordx2 v[194:195], v151, s[14:15] sc1
	v_add_u32_e32 v151, 0x500, v148
	global_load_dwordx2 v[196:197], v151, s[14:15] sc1
	v_add_u32_e32 v151, 0x580, v148
	global_load_dwordx2 v[198:199], v151, s[14:15] sc1
	s_waitcnt vmcnt(0)
	v_ffbh_u32_e32 v151, v185
	v_min_u32_e32 v151, 32, v151
	v_lshlrev_b64 v[184:185], v151, v[184:185]
	v_sub_u32_e32 v151, 32, v151
	v_min_u32_e32 v184, 1, v184
	v_or_b32_e32 v184, v185, v184
	v_cvt_f32_u32_e32 v184, v184
	v_ldexp_f32 v184, v184, v151
	v_fmamk_f32 v184, v184, 0x30800000, v159
	v_mul_f32_e32 v185, 0x4b800000, v184
	v_cmp_gt_f32_e32 vcc, s57, v184
	s_nop 1
	v_cndmask_b32_e32 v184, v184, v185, vcc
	v_rsq_f32_e32 v184, v184
	s_nop 0
	v_mul_f32_e32 v185, 0x45800000, v184
	v_cndmask_b32_e32 v217, v184, v185, vcc
	v_mul_f32_e32 v124, v124, v217
	v_mul_f32_e32 v125, v125, v217
	v_mul_f32_e32 v126, v126, v217
	v_mul_f32_e32 v127, v127, v217
	v_mul_f32_e32 v120, v120, v217
	v_mul_f32_e32 v121, v121, v217
	v_mul_f32_e32 v122, v122, v217
	v_mul_f32_e32 v123, v123, v217
	v_mul_f32_e32 v116, v116, v217
	v_mul_f32_e32 v117, v117, v217
	v_mul_f32_e32 v118, v118, v217
	v_mul_f32_e32 v119, v119, v217
	v_mul_f32_e32 v112, v112, v217
	v_mul_f32_e32 v113, v113, v217
	v_mul_f32_e32 v114, v114, v217
	v_mul_f32_e32 v115, v115, v217
	v_mul_f32_e32 v124, v124, v160
	v_mul_f32_e32 v125, v125, v161
	v_mul_f32_e32 v126, v126, v162
	v_mul_f32_e32 v127, v127, v163
	v_mul_f32_e32 v120, v120, v164
	v_mul_f32_e32 v121, v121, v165
	v_mul_f32_e32 v122, v122, v166
	v_mul_f32_e32 v123, v123, v167
	v_mul_f32_e32 v116, v116, v168
	v_mul_f32_e32 v117, v117, v169
	v_mul_f32_e32 v118, v118, v170
	v_mul_f32_e32 v119, v119, v171
	v_mul_f32_e32 v112, v112, v176
	v_mul_f32_e32 v113, v113, v177
	v_mul_f32_e32 v114, v114, v178
	v_mul_f32_e32 v115, v115, v179
	global_store_dwordx4 v145, v[124:127], s[12:13]
	global_store_dwordx4 v145, v[120:123], s[12:13] offset:16
	global_store_dwordx4 v145, v[116:119], s[12:13] offset:512
	global_store_dwordx4 v145, v[112:115], s[12:13] offset:528
	v_ffbh_u32_e32 v151, v187
	v_min_u32_e32 v151, 32, v151
	v_lshlrev_b64 v[186:187], v151, v[186:187]
	v_sub_u32_e32 v151, 32, v151
	v_min_u32_e32 v186, 1, v186
	v_or_b32_e32 v186, v187, v186
	v_cvt_f32_u32_e32 v186, v186
	v_ldexp_f32 v186, v186, v151
	v_fmamk_f32 v186, v186, 0x30800000, v159
	v_mul_f32_e32 v187, 0x4b800000, v186
	v_cmp_gt_f32_e32 vcc, s57, v186
	s_nop 1
	v_cndmask_b32_e32 v186, v186, v187, vcc
	v_rsq_f32_e32 v186, v186
	s_nop 0
	v_mul_f32_e32 v187, 0x45800000, v186
	v_cndmask_b32_e32 v217, v186, v187, vcc
	v_mul_f32_e32 v108, v108, v217
	v_mul_f32_e32 v109, v109, v217
	v_mul_f32_e32 v110, v110, v217
	v_mul_f32_e32 v111, v111, v217
	v_mul_f32_e32 v104, v104, v217
	v_mul_f32_e32 v105, v105, v217
	v_mul_f32_e32 v106, v106, v217
	v_mul_f32_e32 v107, v107, v217
	v_mul_f32_e32 v100, v100, v217
	v_mul_f32_e32 v101, v101, v217
	v_mul_f32_e32 v102, v102, v217
	v_mul_f32_e32 v103, v103, v217
	v_mul_f32_e32 v96, v96, v217
	v_mul_f32_e32 v97, v97, v217
	v_mul_f32_e32 v98, v98, v217
	v_mul_f32_e32 v99, v99, v217
	v_mul_f32_e32 v108, v108, v160
	v_mul_f32_e32 v109, v109, v161
	v_mul_f32_e32 v110, v110, v162
	v_mul_f32_e32 v111, v111, v163
	v_mul_f32_e32 v104, v104, v164
	v_mul_f32_e32 v105, v105, v165
	v_mul_f32_e32 v106, v106, v166
	v_mul_f32_e32 v107, v107, v167
	v_mul_f32_e32 v100, v100, v168
	v_mul_f32_e32 v101, v101, v169
	v_mul_f32_e32 v102, v102, v170
	v_mul_f32_e32 v103, v103, v171
	v_mul_f32_e32 v96, v96, v176
	v_mul_f32_e32 v97, v97, v177
	v_mul_f32_e32 v98, v98, v178
	v_mul_f32_e32 v99, v99, v179
	v_add_u32_e32 v214, 0x10000, v145
	global_store_dwordx4 v214, v[108:111], s[12:13]
	global_store_dwordx4 v214, v[104:107], s[12:13] offset:16
	global_store_dwordx4 v214, v[100:103], s[12:13] offset:512
	global_store_dwordx4 v214, v[96:99], s[12:13] offset:528
	v_ffbh_u32_e32 v151, v189
	v_min_u32_e32 v151, 32, v151
	v_lshlrev_b64 v[188:189], v151, v[188:189]
	v_sub_u32_e32 v151, 32, v151
	v_min_u32_e32 v188, 1, v188
	v_or_b32_e32 v188, v189, v188
	v_cvt_f32_u32_e32 v188, v188
	v_ldexp_f32 v188, v188, v151
	v_fmamk_f32 v188, v188, 0x30800000, v159
	v_mul_f32_e32 v189, 0x4b800000, v188
	v_cmp_gt_f32_e32 vcc, s57, v188
	s_nop 1
	v_cndmask_b32_e32 v188, v188, v189, vcc
	v_rsq_f32_e32 v188, v188
	s_nop 0
	v_mul_f32_e32 v189, 0x45800000, v188
	v_cndmask_b32_e32 v217, v188, v189, vcc
	v_mul_f32_e32 v92, v92, v217
	v_mul_f32_e32 v93, v93, v217
	v_mul_f32_e32 v94, v94, v217
	v_mul_f32_e32 v95, v95, v217
	v_mul_f32_e32 v88, v88, v217
	v_mul_f32_e32 v89, v89, v217
	v_mul_f32_e32 v90, v90, v217
	v_mul_f32_e32 v91, v91, v217
	v_mul_f32_e32 v84, v84, v217
	v_mul_f32_e32 v85, v85, v217
	v_mul_f32_e32 v86, v86, v217
	v_mul_f32_e32 v87, v87, v217
	v_mul_f32_e32 v80, v80, v217
	v_mul_f32_e32 v81, v81, v217
	v_mul_f32_e32 v82, v82, v217
	v_mul_f32_e32 v83, v83, v217
	v_mul_f32_e32 v92, v92, v160
	v_mul_f32_e32 v93, v93, v161
	v_mul_f32_e32 v94, v94, v162
	v_mul_f32_e32 v95, v95, v163
	v_mul_f32_e32 v88, v88, v164
	v_mul_f32_e32 v89, v89, v165
	v_mul_f32_e32 v90, v90, v166
	v_mul_f32_e32 v91, v91, v167
	v_mul_f32_e32 v84, v84, v168
	v_mul_f32_e32 v85, v85, v169
	v_mul_f32_e32 v86, v86, v170
	v_mul_f32_e32 v87, v87, v171
	v_mul_f32_e32 v80, v80, v176
	v_mul_f32_e32 v81, v81, v177
	v_mul_f32_e32 v82, v82, v178
	v_mul_f32_e32 v83, v83, v179
	v_add_u32_e32 v214, 0x20000, v145
	global_store_dwordx4 v214, v[92:95], s[12:13]
	global_store_dwordx4 v214, v[88:91], s[12:13] offset:16
	global_store_dwordx4 v214, v[84:87], s[12:13] offset:512
	global_store_dwordx4 v214, v[80:83], s[12:13] offset:528
	v_ffbh_u32_e32 v151, v191
	v_min_u32_e32 v151, 32, v151
	v_lshlrev_b64 v[190:191], v151, v[190:191]
	v_sub_u32_e32 v151, 32, v151
	v_min_u32_e32 v190, 1, v190
	v_or_b32_e32 v190, v191, v190
	v_cvt_f32_u32_e32 v190, v190
	v_ldexp_f32 v190, v190, v151
	v_fmamk_f32 v190, v190, 0x30800000, v159
	v_mul_f32_e32 v191, 0x4b800000, v190
	v_cmp_gt_f32_e32 vcc, s57, v190
	s_nop 1
	v_cndmask_b32_e32 v190, v190, v191, vcc
	v_rsq_f32_e32 v190, v190
	s_nop 0
	v_mul_f32_e32 v191, 0x45800000, v190
	v_cndmask_b32_e32 v217, v190, v191, vcc
	v_mul_f32_e32 v76, v76, v217
	v_mul_f32_e32 v77, v77, v217
	v_mul_f32_e32 v78, v78, v217
	v_mul_f32_e32 v79, v79, v217
	v_mul_f32_e32 v72, v72, v217
	v_mul_f32_e32 v73, v73, v217
	v_mul_f32_e32 v74, v74, v217
	v_mul_f32_e32 v75, v75, v217
	v_mul_f32_e32 v68, v68, v217
	v_mul_f32_e32 v69, v69, v217
	v_mul_f32_e32 v70, v70, v217
	v_mul_f32_e32 v71, v71, v217
	v_mul_f32_e32 v64, v64, v217
	v_mul_f32_e32 v65, v65, v217
	v_mul_f32_e32 v66, v66, v217
	v_mul_f32_e32 v67, v67, v217
	v_mul_f32_e32 v76, v76, v160
	v_mul_f32_e32 v77, v77, v161
	v_mul_f32_e32 v78, v78, v162
	v_mul_f32_e32 v79, v79, v163
	v_mul_f32_e32 v72, v72, v164
	v_mul_f32_e32 v73, v73, v165
	v_mul_f32_e32 v74, v74, v166
	v_mul_f32_e32 v75, v75, v167
	v_mul_f32_e32 v68, v68, v168
	v_mul_f32_e32 v69, v69, v169
	v_mul_f32_e32 v70, v70, v170
	v_mul_f32_e32 v71, v71, v171
	v_mul_f32_e32 v64, v64, v176
	v_mul_f32_e32 v65, v65, v177
	v_mul_f32_e32 v66, v66, v178
	v_mul_f32_e32 v67, v67, v179
	v_add_u32_e32 v214, 0x30000, v145
	global_store_dwordx4 v214, v[76:79], s[12:13]
	global_store_dwordx4 v214, v[72:75], s[12:13] offset:16
	global_store_dwordx4 v214, v[68:71], s[12:13] offset:512
	global_store_dwordx4 v214, v[64:67], s[12:13] offset:528
	v_ffbh_u32_e32 v151, v193
	v_min_u32_e32 v151, 32, v151
	v_lshlrev_b64 v[192:193], v151, v[192:193]
	v_sub_u32_e32 v151, 32, v151
	v_min_u32_e32 v192, 1, v192
	v_or_b32_e32 v192, v193, v192
	v_cvt_f32_u32_e32 v192, v192
	v_ldexp_f32 v192, v192, v151
	v_fmamk_f32 v192, v192, 0x30800000, v159
	v_mul_f32_e32 v193, 0x4b800000, v192
	v_cmp_gt_f32_e32 vcc, s57, v192
	s_nop 1
	v_cndmask_b32_e32 v192, v192, v193, vcc
	v_rsq_f32_e32 v192, v192
	s_nop 0
	v_mul_f32_e32 v193, 0x45800000, v192
	v_cndmask_b32_e32 v217, v192, v193, vcc
	v_mul_f32_e32 v60, v60, v217
	v_mul_f32_e32 v61, v61, v217
	v_mul_f32_e32 v62, v62, v217
	v_mul_f32_e32 v63, v63, v217
	v_mul_f32_e32 v56, v56, v217
	v_mul_f32_e32 v57, v57, v217
	v_mul_f32_e32 v58, v58, v217
	v_mul_f32_e32 v59, v59, v217
	v_mul_f32_e32 v52, v52, v217
	v_mul_f32_e32 v53, v53, v217
	v_mul_f32_e32 v54, v54, v217
	v_mul_f32_e32 v55, v55, v217
	v_mul_f32_e32 v48, v48, v217
	v_mul_f32_e32 v49, v49, v217
	v_mul_f32_e32 v50, v50, v217
	v_mul_f32_e32 v51, v51, v217
	v_mul_f32_e32 v60, v60, v160
	v_mul_f32_e32 v61, v61, v161
	v_mul_f32_e32 v62, v62, v162
	v_mul_f32_e32 v63, v63, v163
	v_mul_f32_e32 v56, v56, v164
	v_mul_f32_e32 v57, v57, v165
	v_mul_f32_e32 v58, v58, v166
	v_mul_f32_e32 v59, v59, v167
	v_mul_f32_e32 v52, v52, v168
	v_mul_f32_e32 v53, v53, v169
	v_mul_f32_e32 v54, v54, v170
	v_mul_f32_e32 v55, v55, v171
	v_mul_f32_e32 v48, v48, v176
	v_mul_f32_e32 v49, v49, v177
	v_mul_f32_e32 v50, v50, v178
	v_mul_f32_e32 v51, v51, v179
	v_add_u32_e32 v214, 0x80000, v145
	global_store_dwordx4 v214, v[60:63], s[12:13]
	global_store_dwordx4 v214, v[56:59], s[12:13] offset:16
	global_store_dwordx4 v214, v[52:55], s[12:13] offset:512
	global_store_dwordx4 v214, v[48:51], s[12:13] offset:528
	v_ffbh_u32_e32 v151, v195
	v_min_u32_e32 v151, 32, v151
	v_lshlrev_b64 v[194:195], v151, v[194:195]
	v_sub_u32_e32 v151, 32, v151
	v_min_u32_e32 v194, 1, v194
	v_or_b32_e32 v194, v195, v194
	v_cvt_f32_u32_e32 v194, v194
	v_ldexp_f32 v194, v194, v151
	v_fmamk_f32 v194, v194, 0x30800000, v159
	v_mul_f32_e32 v195, 0x4b800000, v194
	v_cmp_gt_f32_e32 vcc, s57, v194
	s_nop 1
	v_cndmask_b32_e32 v194, v194, v195, vcc
	v_rsq_f32_e32 v194, v194
	s_nop 0
	v_mul_f32_e32 v195, 0x45800000, v194
	v_cndmask_b32_e32 v217, v194, v195, vcc
	v_mul_f32_e32 v44, v44, v217
	v_mul_f32_e32 v45, v45, v217
	v_mul_f32_e32 v46, v46, v217
	v_mul_f32_e32 v47, v47, v217
	v_mul_f32_e32 v40, v40, v217
	v_mul_f32_e32 v41, v41, v217
	v_mul_f32_e32 v42, v42, v217
	v_mul_f32_e32 v43, v43, v217
	v_mul_f32_e32 v36, v36, v217
	v_mul_f32_e32 v37, v37, v217
	v_mul_f32_e32 v38, v38, v217
	v_mul_f32_e32 v39, v39, v217
	v_mul_f32_e32 v32, v32, v217
	v_mul_f32_e32 v33, v33, v217
	v_mul_f32_e32 v34, v34, v217
	v_mul_f32_e32 v35, v35, v217
	v_mul_f32_e32 v44, v44, v160
	v_mul_f32_e32 v45, v45, v161
	v_mul_f32_e32 v46, v46, v162
	v_mul_f32_e32 v47, v47, v163
	v_mul_f32_e32 v40, v40, v164
	v_mul_f32_e32 v41, v41, v165
	v_mul_f32_e32 v42, v42, v166
	v_mul_f32_e32 v43, v43, v167
	v_mul_f32_e32 v36, v36, v168
	v_mul_f32_e32 v37, v37, v169
	v_mul_f32_e32 v38, v38, v170
	v_mul_f32_e32 v39, v39, v171
	v_mul_f32_e32 v32, v32, v176
	v_mul_f32_e32 v33, v33, v177
	v_mul_f32_e32 v34, v34, v178
	v_mul_f32_e32 v35, v35, v179
	v_add_u32_e32 v214, 0x90000, v145
	global_store_dwordx4 v214, v[44:47], s[12:13]
	global_store_dwordx4 v214, v[40:43], s[12:13] offset:16
	global_store_dwordx4 v214, v[36:39], s[12:13] offset:512
	global_store_dwordx4 v214, v[32:35], s[12:13] offset:528
	v_ffbh_u32_e32 v151, v197
	v_min_u32_e32 v151, 32, v151
	v_lshlrev_b64 v[196:197], v151, v[196:197]
	v_sub_u32_e32 v151, 32, v151
	v_min_u32_e32 v196, 1, v196
	v_or_b32_e32 v196, v197, v196
	v_cvt_f32_u32_e32 v196, v196
	v_ldexp_f32 v196, v196, v151
	v_fmamk_f32 v196, v196, 0x30800000, v159
	v_mul_f32_e32 v197, 0x4b800000, v196
	v_cmp_gt_f32_e32 vcc, s57, v196
	s_nop 1
	v_cndmask_b32_e32 v196, v196, v197, vcc
	v_rsq_f32_e32 v196, v196
	s_nop 0
	v_mul_f32_e32 v197, 0x45800000, v196
	v_cndmask_b32_e32 v217, v196, v197, vcc
	v_mul_f32_e32 v28, v28, v217
	v_mul_f32_e32 v29, v29, v217
	v_mul_f32_e32 v30, v30, v217
	v_mul_f32_e32 v31, v31, v217
	v_mul_f32_e32 v24, v24, v217
	v_mul_f32_e32 v25, v25, v217
	v_mul_f32_e32 v26, v26, v217
	v_mul_f32_e32 v27, v27, v217
	v_mul_f32_e32 v20, v20, v217
	v_mul_f32_e32 v21, v21, v217
	v_mul_f32_e32 v22, v22, v217
	v_mul_f32_e32 v23, v23, v217
	v_mul_f32_e32 v16, v16, v217
	v_mul_f32_e32 v17, v17, v217
	v_mul_f32_e32 v18, v18, v217
	v_mul_f32_e32 v19, v19, v217
	v_mul_f32_e32 v28, v28, v160
	v_mul_f32_e32 v29, v29, v161
	v_mul_f32_e32 v30, v30, v162
	v_mul_f32_e32 v31, v31, v163
	v_mul_f32_e32 v24, v24, v164
	v_mul_f32_e32 v25, v25, v165
	v_mul_f32_e32 v26, v26, v166
	v_mul_f32_e32 v27, v27, v167
	v_mul_f32_e32 v20, v20, v168
	v_mul_f32_e32 v21, v21, v169
	v_mul_f32_e32 v22, v22, v170
	v_mul_f32_e32 v23, v23, v171
	v_mul_f32_e32 v16, v16, v176
	v_mul_f32_e32 v17, v17, v177
	v_mul_f32_e32 v18, v18, v178
	v_mul_f32_e32 v19, v19, v179
	v_add_u32_e32 v214, 0xa0000, v145
	global_store_dwordx4 v214, v[28:31], s[12:13]
	global_store_dwordx4 v214, v[24:27], s[12:13] offset:16
	global_store_dwordx4 v214, v[20:23], s[12:13] offset:512
	global_store_dwordx4 v214, v[16:19], s[12:13] offset:528
	v_ffbh_u32_e32 v151, v199
	v_min_u32_e32 v151, 32, v151
	v_lshlrev_b64 v[198:199], v151, v[198:199]
	v_sub_u32_e32 v151, 32, v151
	v_min_u32_e32 v198, 1, v198
	v_or_b32_e32 v198, v199, v198
	v_cvt_f32_u32_e32 v198, v198
	v_ldexp_f32 v198, v198, v151
	v_fmamk_f32 v198, v198, 0x30800000, v159
	v_mul_f32_e32 v199, 0x4b800000, v198
	v_cmp_gt_f32_e32 vcc, s57, v198
	s_nop 1
	v_cndmask_b32_e32 v198, v198, v199, vcc
	v_rsq_f32_e32 v198, v198
	s_nop 0
	v_mul_f32_e32 v199, 0x45800000, v198
	v_cndmask_b32_e32 v217, v198, v199, vcc
	v_mul_f32_e32 v12, v12, v217
	v_mul_f32_e32 v13, v13, v217
	v_mul_f32_e32 v14, v14, v217
	v_mul_f32_e32 v15, v15, v217
	v_mul_f32_e32 v8, v8, v217
	v_mul_f32_e32 v9, v9, v217
	v_mul_f32_e32 v10, v10, v217
	v_mul_f32_e32 v11, v11, v217
	v_mul_f32_e32 v4, v4, v217
	v_mul_f32_e32 v5, v5, v217
	v_mul_f32_e32 v6, v6, v217
	v_mul_f32_e32 v7, v7, v217
	v_mul_f32_e32 v0, v0, v217
	v_mul_f32_e32 v1, v1, v217
	v_mul_f32_e32 v2, v2, v217
	v_mul_f32_e32 v3, v3, v217
	v_mul_f32_e32 v12, v12, v160
	v_mul_f32_e32 v13, v13, v161
	v_mul_f32_e32 v14, v14, v162
	v_mul_f32_e32 v15, v15, v163
	v_mul_f32_e32 v8, v8, v164
	v_mul_f32_e32 v9, v9, v165
	v_mul_f32_e32 v10, v10, v166
	v_mul_f32_e32 v11, v11, v167
	v_mul_f32_e32 v4, v4, v168
	v_mul_f32_e32 v5, v5, v169
	v_mul_f32_e32 v6, v6, v170
	v_mul_f32_e32 v7, v7, v171
	v_mul_f32_e32 v0, v0, v176
	v_mul_f32_e32 v1, v1, v177
	v_mul_f32_e32 v2, v2, v178
	v_mul_f32_e32 v3, v3, v179
	v_add_u32_e32 v214, 0xb0000, v145
	global_store_dwordx4 v214, v[12:15], s[12:13]
	global_store_dwordx4 v214, v[8:11], s[12:13] offset:16
	global_store_dwordx4 v214, v[4:7], s[12:13] offset:512
	global_store_dwordx4 v214, v[0:3], s[12:13] offset:528

.LBB0_2063:
	s_endpgm
	s_waitcnt vmcnt(0)
	s_waitcnt lgkmcnt(0)
	s_barrier
	s_mov_b64 s[2:3], exec
	v_readlane_b32 s4, v246, 2
	v_readlane_b32 s5, v246, 3
	s_and_b64 s[4:5], s[2:3], s[4:5]
	s_mov_b64 exec, s[4:5]
	s_cbranch_execz .LBB0_2115
	s_add_i32 s4, 0, 0x20040
	v_mov_b32_e32 v0, s4
	s_waitcnt vmcnt(0) expcnt(0) lgkmcnt(0)
	ds_read_b32 v2, v0
	s_add_i32 s4, 0, 0x20044
	v_mov_b32_e32 v0, s4
	ds_read_b32 v0, v0
	s_waitcnt lgkmcnt(1)
	v_cmp_ne_u32_e32 vcc, 0, v2
	s_cbranch_vccnz .LBB0_2079
	s_load_dword s4, s[0:1], 0x138
	s_mov_b32 s47, 1
	v_mov_b32_e32 v16, 0
	s_waitcnt lgkmcnt(0)
	s_mul_i32 s46, s71, s4
	s_add_u32 s4, s66, 0xe0200
	s_addc_u32 s5, s67, 0
	s_add_u32 s6, s66, 0xe0400
	s_addc_u32 s7, s67, 0
	s_add_u32 s8, s66, 0xe0500
	s_addc_u32 s9, s67, 0
	s_add_u32 s10, s66, 0xe0600
	s_addc_u32 s11, s67, 0
	s_add_u32 s12, s66, 0xe0700
	s_addc_u32 s13, s67, 0
	s_add_u32 s14, s66, 0xe0800
	s_addc_u32 s15, s67, 0
	s_add_u32 s16, s66, 0xe0900
	s_addc_u32 s17, s67, 0
	s_add_u32 s18, s66, 0xe0a00
	s_addc_u32 s19, s67, 0
	s_add_u32 s20, s66, 0xe0b00
	s_addc_u32 s21, s67, 0
	s_add_u32 s22, s66, 0xe0c00
	s_addc_u32 s23, s67, 0
	s_add_u32 s24, s66, 0xe0d00
	s_addc_u32 s25, s67, 0
	s_add_u32 s26, s66, 0xe0e00
	s_addc_u32 s27, s67, 0
	s_add_u32 s28, s66, 0xe0f00
	s_addc_u32 s29, s67, 0
	s_add_u32 s30, s66, 0xe1000
	s_addc_u32 s31, s67, 0
	s_add_u32 s34, s66, 0xe1100
	s_addc_u32 s35, s67, 0
	s_add_u32 s36, s66, 0xe1200
	s_addc_u32 s37, s67, 0
	s_add_u32 s38, s66, 0xe1300
	s_mul_i32 s46, s46, s70
	s_addc_u32 s39, s67, 0
	s_branch .LBB0_2067
